# attention / gate: adjacent 32x32x16 MFMA runs regrouped by accumulator (chains), and MFMA+operand-reload blocks swapped so same-accumulator MFMAs are back to back; on top of v53
# speedup vs baseline: 1.0816x; 1.0816x over previous
; #define PV_LD(R, d0) do { constexpr int b_ = v_rd_off(d0, 0, 0); TRRD(R##0, b_); TRRD(R##1, b_ + 2048); TRRD(R##2, b_ + 4096); TRRD(R##3, b_ + 6144); TRRD(R##4, b_ + 8192); TRRD(R##5, b_ + 10240); TRRD(R##6, b_ + 12288); TRRD(R##7, b_ + 14336); } while (0)
; #define PV_MM(R, d0) do { o[d0] = __builtin_amdgcn_mfma_f32_32x32x16_bf16(PV_J(R##0, R##1), pa0, o[d0], 0, 0, 0); o[d0] = __builtin_amdgcn_mfma_f32_32x32x16_bf16(PV_J(R##2, R##3), pa1, o[d0], 0, 0, 0); \
;         o[d0] = __builtin_amdgcn_mfma_f32_32x32x16_bf16(PV_J(R##4, R##5), pa2, o[d0], 0, 0, 0); o[d0] = __builtin_amdgcn_mfma_f32_32x32x16_bf16(PV_J(R##6, R##7), pa3, o[d0], 0, 0, 0); } while (0)
; #define PV_W(n, R) asm volatile("s_waitcnt lgkmcnt(" #n ")" : "+v"(R##0), "+v"(R##1), "+v"(R##2), "+v"(R##3), "+v"(R##4), "+v"(R##5), "+v"(R##6), "+v"(R##7) :: "memory")
; __device__ __forceinline__ void partialSM(f32x16& p0, f32x16& p1, float& m_reg, float& mn, float& alpha) {
;     ...
;     else { mn = fmaxf(m_reg, pmax); alpha = __builtin_amdgcn_exp2f(m_reg - mn); m_reg = mn; }
;     p0 = p0 - mn; p1 = p1 - mn;
;     for (int r = 0; r < 16; ++r) p0[r] = __builtin_amdgcn_exp2f(p0[r]);
; }
; __device__ __forceinline__ void finishSM(f32x16& p0, f32x16& p1, float alpha, float& l_reg, bf16x8& pa0, bf16x8& pa1, bf16x8& pa2, bf16x8& pa3) {
;     for (int r = 0; r < 16; ++r) p1[r] = __builtin_amdgcn_exp2f(p1[r]);
;     typedef float f32x8_ __attribute__((ext_vector_type(8))); typedef float f32x2_ __attribute__((ext_vector_type(2)));
;     const f32x16 s16 = p0 + p1; const f32x8_ s8 = s16.lo + s16.hi; const f32x4 s4 = s8.lo + s8.hi; const f32x2_ s2 = s4.lo + s4.hi; float ps = s2.x + s2.y;
;     { auto rr = __builtin_amdgcn_permlane32_swap(__float_as_uint(ps), __float_as_uint(ps), false, false);
;       ps = __uint_as_float(rr[0]) + __uint_as_float(rr[1]); }
;     l_reg = l_reg * alpha + ps;
;     ...
;     PK4(p0, 0, pa0); PK4(p0, 8, pa1); PK4(p1, 0, pa2); PK4(p1, 8, pa3);
;     ...
; }
; template <bool SK>
; __device__ __forceinline__ void pv_tile_x(f32x16* o, int vb, bf16x8 pa0, bf16x8 pa1, bf16x8 pa2, bf16x8 pa3, bool act) {
;     ...
;     s16x4 fa0, fa1, fa2, fa3, fa4, fa5, fa6, fa7, fb0, fb1, fb2, fb3, fb4, fb5, fb6, fb7;
;     PV_LD(fa, 0); PV_LD(fb, 1);
;     PV_W(8, fa); PV_MM(fa, 0); PV_LD(fa, 2);
;     PV_W(8, fb); PV_MM(fb, 1); PV_LD(fb, 3);
;     PV_W(8, fa); PV_MM(fa, 2);
;     PV_W(0, fb); PV_MM(fb, 3);
.LBB0_960:
	v_sub_f32_e32 v67, v113, v157
	v_sub_f32_e32 v112, v112, v157
	v_sub_f32_e32 v111, v111, v157
	v_sub_f32_e32 v110, v110, v157
	v_sub_f32_e32 v81, v109, v157
	v_sub_f32_e32 v80, v108, v157
	v_sub_f32_e32 v79, v107, v157
	v_sub_f32_e32 v78, v106, v157
	v_sub_f32_e32 v77, v105, v157
	v_sub_f32_e32 v76, v104, v157
	v_sub_f32_e32 v75, v103, v157
	v_sub_f32_e32 v74, v102, v157
	v_sub_f32_e32 v73, v101, v157
	v_sub_f32_e32 v72, v100, v157
	v_sub_f32_e32 v71, v99, v157
	v_sub_f32_e32 v70, v98, v157
	v_sub_f32_e32 v99, v97, v157
	v_sub_f32_e32 v100, v96, v157
	v_sub_f32_e32 v102, v95, v157
	v_sub_f32_e32 v98, v94, v157
	v_sub_f32_e32 v97, v93, v157
	v_sub_f32_e32 v96, v92, v157
	v_sub_f32_e32 v95, v91, v157
	v_sub_f32_e32 v94, v90, v157
	v_sub_f32_e32 v93, v89, v157
	v_sub_f32_e32 v92, v88, v157
	v_sub_f32_e32 v91, v87, v157
	v_sub_f32_e32 v90, v86, v157
	v_sub_f32_e32 v89, v85, v157
	v_sub_f32_e32 v88, v84, v157
	v_sub_f32_e32 v87, v83, v157
	v_sub_f32_e32 v86, v82, v157
	v_exp_f32_e32 v70, v70
	v_exp_f32_e32 v71, v71
	v_exp_f32_e32 v72, v72
	v_exp_f32_e32 v73, v73
	v_exp_f32_e32 v74, v74
	v_exp_f32_e32 v75, v75
	v_exp_f32_e32 v76, v76
	v_exp_f32_e32 v77, v77
	v_exp_f32_e32 v78, v78
	v_exp_f32_e32 v79, v79
	v_exp_f32_e32 v80, v80
	v_exp_f32_e32 v81, v81
	v_exp_f32_e32 v82, v110
	v_exp_f32_e32 v83, v111
	v_exp_f32_e32 v84, v112
	v_exp_f32_e32 v85, v67
	v_exp_f32_e32 v86, v86
	v_exp_f32_e32 v87, v87
	v_exp_f32_e32 v88, v88
	v_exp_f32_e32 v89, v89
	v_exp_f32_e32 v90, v90
	v_exp_f32_e32 v91, v91
	v_exp_f32_e32 v92, v92
	v_exp_f32_e32 v93, v93
	v_exp_f32_e32 v94, v94
	v_exp_f32_e32 v95, v95
	v_exp_f32_e32 v96, v96
	v_exp_f32_e32 v97, v97
	v_exp_f32_e32 v98, v98
	v_exp_f32_e32 v100, v100
	v_exp_f32_e32 v101, v99
	v_exp_f32_e32 v99, v102
	v_add_f32_e32 v1, v66, v1
	v_pk_add_f32 v[66:67], v[96:97], v[80:81]
	v_pk_add_f32 v[102:103], v[88:89], v[72:73]
	v_pk_add_f32 v[104:105], v[100:101], v[84:85]
	v_pk_add_f32 v[106:107], v[92:93], v[76:77]
	v_pk_add_f32 v[108:109], v[94:95], v[78:79]
	v_pk_add_f32 v[110:111], v[86:87], v[70:71]
	v_pk_add_f32 v[112:113], v[98:99], v[82:83]
	v_pk_add_f32 v[148:149], v[90:91], v[74:75]
	v_pk_add_f32 v[108:109], v[110:111], v[108:109]
	v_pk_add_f32 v[112:113], v[148:149], v[112:113]
	v_pk_add_f32 v[104:105], v[106:107], v[104:105]
	v_pk_add_f32 v[66:67], v[102:103], v[66:67]
	v_pk_add_f32 v[102:103], v[108:109], v[112:113]
	v_pk_add_f32 v[66:67], v[66:67], v[104:105]
	s_xor_b32 s78, s78, 1
	v_pk_add_f32 v[66:67], v[102:103], v[66:67]
	v_cvt_pk_bf16_f32 v70, v70, v71
	v_cvt_pk_bf16_f32 v71, v72, v73
	v_cvt_pk_bf16_f32 v72, v74, v75
	v_cvt_pk_bf16_f32 v73, v76, v77
	v_cvt_pk_bf16_f32 v74, v78, v79
	s_nop 0
	v_pk_add_f32 v[66:67], v[66:67], v[66:67] op_sel:[0,1] op_sel_hi:[1,0]
	v_cvt_pk_bf16_f32 v75, v80, v81
	v_cvt_pk_bf16_f32 v76, v82, v83
	v_cvt_pk_bf16_f32 v77, v84, v85
	v_cvt_pk_bf16_f32 v78, v86, v87
	v_cvt_pk_bf16_f32 v79, v88, v89
	s_nop 0
	v_mov_b32_e32 v67, v66
	v_cvt_pk_bf16_f32 v80, v90, v91
	v_cvt_pk_bf16_f32 v81, v92, v93
	v_cvt_pk_bf16_f32 v82, v94, v95
	v_cvt_pk_bf16_f32 v83, v96, v97
	v_cvt_pk_bf16_f32 v84, v98, v99
	v_cvt_pk_bf16_f32 v85, v100, v101
	v_lshlrev_b32_e32 v69, 3, v161
	v_fmac_f32_e32 v1, v191, v158
	v_permlane32_swap_b32_e32 v66, v67
	v_permlane32_swap_b32_e32 v70, v72
	v_permlane32_swap_b32_e32 v71, v73
	v_permlane32_swap_b32_e32 v74, v76
	v_permlane32_swap_b32_e32 v75, v77
	v_permlane32_swap_b32_e32 v78, v80
	v_permlane32_swap_b32_e32 v79, v81
	v_permlane32_swap_b32_e32 v82, v84
	v_permlane32_swap_b32_e32 v83, v85
	v_add_u32_e32 v152, s19, v171
	ds_read_b64_tr_b16 v[86:87], v152 offset:0
	ds_read_b64_tr_b16 v[88:89], v152 offset:0x800
	ds_read_b64_tr_b16 v[90:91], v152 offset:0x1000
	ds_read_b64_tr_b16 v[92:93], v152 offset:0x1800
	ds_read_b64_tr_b16 v[94:95], v152 offset:0x2000
	ds_read_b64_tr_b16 v[96:97], v152 offset:0x2800
	ds_read_b64_tr_b16 v[98:99], v152 offset:0x3000
	ds_read_b64_tr_b16 v[100:101], v152 offset:0x3800
	ds_read_b64_tr_b16 v[102:103], v152 offset:0x200
	ds_read_b64_tr_b16 v[104:105], v152 offset:0xa00
	ds_read_b64_tr_b16 v[106:107], v152 offset:0x1200
	ds_read_b64_tr_b16 v[108:109], v152 offset:0x1a00
	ds_read_b64_tr_b16 v[110:111], v152 offset:0x2200
	ds_read_b64_tr_b16 v[112:113], v152 offset:0x2a00
	ds_read_b64_tr_b16 v[148:149], v152 offset:0x3200
	ds_read_b64_tr_b16 v[150:151], v152 offset:0x3a00
	s_nop 0
	s_waitcnt lgkmcnt(8)
	v_add_f32_e32 v66, v66, v67
	v_mfma_f32_32x32x16_bf16 v[50:65], v[86:89], v[70:73], v[50:65]
	ds_read_b64_tr_b16 v[86:87], v152 offset:0x400
	ds_read_b64_tr_b16 v[88:89], v152 offset:0xc00
	v_fmac_f32_e32 v66, v1, v68
	v_mfma_f32_32x32x16_bf16 v[50:65], v[90:93], v[74:77], v[50:65]
	ds_read_b64_tr_b16 v[90:91], v152 offset:0x1400
	ds_read_b64_tr_b16 v[92:93], v152 offset:0x1c00
	v_mfma_f32_32x32x16_bf16 v[50:65], v[94:97], v[78:81], v[50:65]
	ds_read_b64_tr_b16 v[94:95], v152 offset:0x2400
	ds_read_b64_tr_b16 v[96:97], v152 offset:0x2c00
	v_mfma_f32_32x32x16_bf16 v[50:65], v[98:101], v[82:85], v[50:65]
	ds_read_b64_tr_b16 v[98:99], v152 offset:0x3400
	ds_read_b64_tr_b16 v[100:101], v152 offset:0x3c00
	s_waitcnt lgkmcnt(8)
; #define PV_LD(R, d0) do { constexpr int b_ = v_rd_off(d0, 0, 0); TRRD(R##0, b_); TRRD(R##1, b_ + 2048); TRRD(R##2, b_ + 4096); TRRD(R##3, b_ + 6144); TRRD(R##4, b_ + 8192); TRRD(R##5, b_ + 10240); TRRD(R##6, b_ + 12288); TRRD(R##7, b_ + 14336); } while (0)
; #define PV_MM(R, d0) do { o[d0] = __builtin_amdgcn_mfma_f32_32x32x16_bf16(PV_J(R##0, R##1), pa0, o[d0], 0, 0, 0); o[d0] = __builtin_amdgcn_mfma_f32_32x32x16_bf16(PV_J(R##2, R##3), pa1, o[d0], 0, 0, 0); \
;         o[d0] = __builtin_amdgcn_mfma_f32_32x32x16_bf16(PV_J(R##4, R##5), pa2, o[d0], 0, 0, 0); o[d0] = __builtin_amdgcn_mfma_f32_32x32x16_bf16(PV_J(R##6, R##7), pa3, o[d0], 0, 0, 0); } while (0)
; #define PV_W(n, R) asm volatile("s_waitcnt lgkmcnt(" #n ")" : "+v"(R##0), "+v"(R##1), "+v"(R##2), "+v"(R##3), "+v"(R##4), "+v"(R##5), "+v"(R##6), "+v"(R##7) :: "memory")
; template <bool SK>
; __device__ __forceinline__ void pv_tile_x(f32x16* o, int vb, bf16x8 pa0, bf16x8 pa1, bf16x8 pa2, bf16x8 pa3, bool act) {
;     ...
;     s16x4 fa0, fa1, fa2, fa3, fa4, fa5, fa6, fa7, fb0, fb1, fb2, fb3, fb4, fb5, fb6, fb7;
;     PV_LD(fa, 0); PV_LD(fb, 1);
;     PV_W(8, fa); PV_MM(fa, 0); PV_LD(fa, 2);
;     PV_W(8, fb); PV_MM(fb, 1); PV_LD(fb, 3);
;     PV_W(8, fa); PV_MM(fa, 2);
;     PV_W(0, fb); PV_MM(fb, 3);
; template <class TIn, class TOut>
; __device__ __forceinline__ void causal_swa_block(const BlockRef<TIn, TOut>& cur, const BlockRef<TIn, TOut>& nxt, int skv, int W, char* lds, Seam<TIn>& S) {
;     ...
;     { const float rl = __builtin_amdgcn_rcpf(l_reg);
;       TOut* Ow = cur.O + (size_t)(wid * QBLK + r32) * OPITCH + 8 * hi;
; #pragma unroll
;       for (int d0 = 0; d0 < 4; ++d0) { const f32x16 v = o[d0] * rl;
; #pragma unroll
;         for (int hf = 0; hf < 2; ++hf) { const unsigned a0 = cvtpk(v[8 * hf + 0], v[8 * hf + 1]), a1 = cvtpk(v[8 * hf + 2], v[8 * hf + 3]), b0_ = cvtpk(v[8 * hf + 4], v[8 * hf + 5]), b1_ = cvtpk(v[8 * hf + 6], v[8 * hf + 7]);
;             auto r0 = __builtin_amdgcn_permlane32_swap(a0, b0_, false, false); auto r1 = __builtin_amdgcn_permlane32_swap(a1, b1_, false, false);
;             u32x4 w = {r0[0], r1[0], r0[1], r1[1]};
;             *(u32x4*)(Ow + d0 * 32 + 16 * hf) = w; } } }
	s_nop 0
	v_mfma_f32_32x32x16_bf16 v[34:49], v[102:105], v[70:73], v[34:49]
	ds_read_b64_tr_b16 v[102:103], v152 offset:0x600
	ds_read_b64_tr_b16 v[104:105], v152 offset:0xe00
	v_mfma_f32_32x32x16_bf16 v[34:49], v[106:109], v[74:77], v[34:49]
	ds_read_b64_tr_b16 v[106:107], v152 offset:0x1600
	ds_read_b64_tr_b16 v[108:109], v152 offset:0x1e00
	v_mfma_f32_32x32x16_bf16 v[34:49], v[110:113], v[78:81], v[34:49]
	ds_read_b64_tr_b16 v[110:111], v152 offset:0x2600
	ds_read_b64_tr_b16 v[112:113], v152 offset:0x2e00
	v_mfma_f32_32x32x16_bf16 v[34:49], v[148:151], v[82:85], v[34:49]
	ds_read_b64_tr_b16 v[148:149], v152 offset:0x3600
	ds_read_b64_tr_b16 v[150:151], v152 offset:0x3e00
	s_waitcnt lgkmcnt(8)
	s_nop 0
	s_waitcnt lgkmcnt(0)
	v_mfma_f32_32x32x16_bf16 v[18:33], v[86:89], v[70:73], v[18:33]
	v_mfma_f32_32x32x16_bf16 v[18:33], v[90:93], v[74:77], v[18:33]
	v_mfma_f32_32x32x16_bf16 v[18:33], v[94:97], v[78:81], v[18:33]
	v_mfma_f32_32x32x16_bf16 v[18:33], v[98:101], v[82:85], v[18:33]
	v_mfma_f32_32x32x16_bf16 v[2:17], v[102:105], v[70:73], v[2:17]
	v_mfma_f32_32x32x16_bf16 v[2:17], v[106:109], v[74:77], v[2:17]
	v_mfma_f32_32x32x16_bf16 v[2:17], v[110:113], v[78:81], v[2:17]
	v_mfma_f32_32x32x16_bf16 v[2:17], v[148:151], v[82:85], v[2:17]
	v_rcp_f32_e32 v68, v66
	v_lshlrev_b64 v[66:67], 12, v[146:147]
	v_lshl_add_u64 v[66:67], s[66:67], 0, v[66:67]
	v_lshlrev_b32_e32 v182, 1, v69
	v_pk_mul_f32 v[52:53], v[68:69], v[52:53] op_sel_hi:[0,1]
	v_pk_mul_f32 v[50:51], v[68:69], v[50:51] op_sel_hi:[0,1]
	v_pk_mul_f32 v[56:57], v[68:69], v[56:57] op_sel_hi:[0,1]
	v_pk_mul_f32 v[54:55], v[68:69], v[54:55] op_sel_hi:[0,1]
	v_cvt_pk_bf16_f32 v50, v50, v51
	v_cvt_pk_bf16_f32 v51, v52, v53
	v_cvt_pk_bf16_f32 v52, v54, v55
	v_cvt_pk_bf16_f32 v53, v56, v57
	v_lshl_add_u64 v[66:67], v[66:67], 0, v[182:183]
	v_permlane32_swap_b32_e32 v50, v52
	v_permlane32_swap_b32_e32 v51, v53
	v_pk_mul_f32 v[64:65], v[68:69], v[64:65] op_sel_hi:[0,1]
	v_pk_mul_f32 v[62:63], v[68:69], v[62:63] op_sel_hi:[0,1]
	v_pk_mul_f32 v[60:61], v[68:69], v[60:61] op_sel_hi:[0,1]
	v_pk_mul_f32 v[58:59], v[68:69], v[58:59] op_sel_hi:[0,1]
	global_store_dwordx4 v[66:67], v[50:53], off
	v_pk_mul_f32 v[36:37], v[68:69], v[36:37] op_sel_hi:[0,1]
	v_pk_mul_f32 v[34:35], v[68:69], v[34:35] op_sel_hi:[0,1]
	v_cvt_pk_bf16_f32 v50, v58, v59
	v_cvt_pk_bf16_f32 v51, v60, v61
	v_cvt_pk_bf16_f32 v52, v62, v63
	v_cvt_pk_bf16_f32 v53, v64, v65
	v_pk_mul_f32 v[40:41], v[68:69], v[40:41] op_sel_hi:[0,1]
	v_permlane32_swap_b32_e32 v50, v52
	v_permlane32_swap_b32_e32 v51, v53
	global_store_dwordx4 v[66:67], v[50:53], off offset:32
	v_pk_mul_f32 v[38:39], v[68:69], v[38:39] op_sel_hi:[0,1]
	v_cvt_pk_bf16_f32 v34, v34, v35
	v_cvt_pk_bf16_f32 v35, v36, v37
	v_cvt_pk_bf16_f32 v36, v38, v39
	v_cvt_pk_bf16_f32 v37, v40, v41
	v_pk_mul_f32 v[48:49], v[68:69], v[48:49] op_sel_hi:[0,1]
	v_permlane32_swap_b32_e32 v34, v36
	v_permlane32_swap_b32_e32 v35, v37
	v_pk_mul_f32 v[46:47], v[68:69], v[46:47] op_sel_hi:[0,1]
	v_pk_mul_f32 v[44:45], v[68:69], v[44:45] op_sel_hi:[0,1]
	v_pk_mul_f32 v[42:43], v[68:69], v[42:43] op_sel_hi:[0,1]
	global_store_dwordx4 v[66:67], v[34:37], off offset:64
	v_pk_mul_f32 v[20:21], v[68:69], v[20:21] op_sel_hi:[0,1]
	v_pk_mul_f32 v[18:19], v[68:69], v[18:19] op_sel_hi:[0,1]
	v_cvt_pk_bf16_f32 v34, v42, v43
	v_cvt_pk_bf16_f32 v35, v44, v45
	v_cvt_pk_bf16_f32 v36, v46, v47
	v_cvt_pk_bf16_f32 v37, v48, v49
	v_pk_mul_f32 v[24:25], v[68:69], v[24:25] op_sel_hi:[0,1]
	v_permlane32_swap_b32_e32 v34, v36
	v_permlane32_swap_b32_e32 v35, v37
	global_store_dwordx4 v[66:67], v[34:37], off offset:96
	v_pk_mul_f32 v[22:23], v[68:69], v[22:23] op_sel_hi:[0,1]
	v_cvt_pk_bf16_f32 v18, v18, v19
	v_cvt_pk_bf16_f32 v19, v20, v21
	v_cvt_pk_bf16_f32 v20, v22, v23
	v_cvt_pk_bf16_f32 v21, v24, v25
	v_pk_mul_f32 v[32:33], v[68:69], v[32:33] op_sel_hi:[0,1]
	v_permlane32_swap_b32_e32 v18, v20
	v_permlane32_swap_b32_e32 v19, v21
	v_pk_mul_f32 v[30:31], v[68:69], v[30:31] op_sel_hi:[0,1]
	v_pk_mul_f32 v[28:29], v[68:69], v[28:29] op_sel_hi:[0,1]
	v_pk_mul_f32 v[26:27], v[68:69], v[26:27] op_sel_hi:[0,1]
	global_store_dwordx4 v[66:67], v[18:21], off offset:128
	v_pk_mul_f32 v[4:5], v[68:69], v[4:5] op_sel_hi:[0,1]
	v_pk_mul_f32 v[2:3], v[68:69], v[2:3] op_sel_hi:[0,1]
	v_cvt_pk_bf16_f32 v18, v26, v27
	v_cvt_pk_bf16_f32 v19, v28, v29
	v_cvt_pk_bf16_f32 v20, v30, v31
	v_cvt_pk_bf16_f32 v21, v32, v33
	v_pk_mul_f32 v[8:9], v[68:69], v[8:9] op_sel_hi:[0,1]
	v_permlane32_swap_b32_e32 v18, v20
	v_permlane32_swap_b32_e32 v19, v21
	global_store_dwordx4 v[66:67], v[18:21], off offset:160
	v_pk_mul_f32 v[6:7], v[68:69], v[6:7] op_sel_hi:[0,1]
	v_cvt_pk_bf16_f32 v2, v2, v3
	v_cvt_pk_bf16_f32 v3, v4, v5
	v_cvt_pk_bf16_f32 v4, v6, v7
	v_cvt_pk_bf16_f32 v5, v8, v9
	v_pk_mul_f32 v[16:17], v[68:69], v[16:17] op_sel_hi:[0,1]
	v_permlane32_swap_b32_e32 v2, v4
	v_permlane32_swap_b32_e32 v3, v5
	v_pk_mul_f32 v[14:15], v[68:69], v[14:15] op_sel_hi:[0,1]
	v_pk_mul_f32 v[12:13], v[68:69], v[12:13] op_sel_hi:[0,1]
	v_pk_mul_f32 v[10:11], v[68:69], v[10:11] op_sel_hi:[0,1]
	global_store_dwordx4 v[66:67], v[2:5], off offset:192
	s_andn2_b64 vcc, exec, s[12:13]
	s_mov_b32 s35, s7
	v_cvt_pk_bf16_f32 v2, v10, v11
	v_cvt_pk_bf16_f32 v3, v12, v13
	v_cvt_pk_bf16_f32 v4, v14, v15
	v_cvt_pk_bf16_f32 v5, v16, v17
	s_mov_b64 s[66:67], s[14:15]
	v_permlane32_swap_b32_e32 v2, v4
	v_permlane32_swap_b32_e32 v3, v5
	global_store_dwordx4 v[66:67], v[2:5], off offset:224
	s_waitcnt vmcnt(0)
	s_mov_b64 s[70:71], s[64:65]
	s_mov_b64 s[68:69], s[62:63]
	s_waitcnt vmcnt(0) lgkmcnt(0)
	s_barrier
	s_cbranch_vccz .LBB0_1010

; #define K_LD(R, A0, A1, off) do { KRD(R##0, A0, off); KRD(R##1, A0, off + 8192); KRD(R##2, A1, off); KRD(R##3, A1, off + 8192); } while (0)
; #define K_MM(R, d) do { p0 = __builtin_amdgcn_mfma_f32_32x32x16_bf16(R##0, qr[d + 0], p0, 0, 0, 0); p1 = __builtin_amdgcn_mfma_f32_32x32x16_bf16(R##1, qr[d + 0], p1, 0, 0, 0); \
;         p0 = __builtin_amdgcn_mfma_f32_32x32x16_bf16(R##2, qr[d + 1], p0, 0, 0, 0); p1 = __builtin_amdgcn_mfma_f32_32x32x16_bf16(R##3, qr[d + 1], p1, 0, 0, 0); } while (0)
; #define K_W(n, R) asm volatile("s_waitcnt lgkmcnt(" #n ")" : "+v"(R##0), "+v"(R##1), "+v"(R##2), "+v"(R##3) :: "memory")
; __device__ __forceinline__ void mask_tile(f32x16& p0, f32x16& p1, int dq, unsigned W) {
;     const float NEG = -__builtin_inff();
; #pragma unroll
;     for (int r = 0; r < 16; ++r) {
;         const int c = (r & 3) + 8 * (r >> 2);
;         if ((unsigned)(dq - c) >= W) p0[r] = NEG;
;         if ((unsigned)(dq - c - 32) >= W) p1[r] = NEG;
;     }
; }
; template <bool SK>
; __device__ __forceinline__ void qkt_x(f32x16& p0, f32x16& p1, const char* K_lds, int r32, int hi, const bf16x8* qr, bool act, const char* fb) {
;     const int k0a = (int)(uintptr_t)K_lds + KSWZ(r32, (0 * 16 + hi * 8) * 2), k1a = (int)(uintptr_t)K_lds + KSWZ(r32, (1 * 16 + hi * 8) * 2), k2a = (int)(uintptr_t)K_lds + KSWZ(r32, (2 * 16 + hi * 8) * 2), k3a = (int)(uintptr_t)K_lds + KSWZ(r32, (3 * 16 + hi * 8) * 2);
;     ...
;     bf16x8 ka0, ka1, ka2, ka3, kb0, kb1, kb2, kb3;
;     K_LD(ka, k0a, k1a, 0); K_LD(kb, k2a, k3a, 0);
; #pragma unroll
;     for (int q = 0; q < 4; ++q) { const f32x4 b0 = *reinterpret_cast<const f32x4*>(fb + q * 32), b1 = *reinterpret_cast<const f32x4*>(fb + 128 + q * 32);
; #pragma unroll
;         for (int i = 0; i < 4; ++i) { p0[4 * q + i] = b0[i]; p1[4 * q + i] = b1[i]; } }
;     K_W(12, ka);
;     K_MM(ka, 0); K_LD(ka, k0a, k1a, 128);
;     K_W(4, kb); K_MM(kb, 2); K_LD(kb, k2a, k3a, 128);
;     K_W(4, ka); K_MM(ka, 4);
;     K_W(0, kb); K_MM(kb, 6);
.LBB0_975:
	v_lshrrev_b32_e32 v161, 5, v1
	v_lshlrev_b32_e32 v42, 2, v161
	v_lshlrev_b32_e32 v148, 4, v161
	s_add_i32 s19, s19, s35
	v_sub_u32_e32 v2, v35, v42
	v_add_u32_e32 v192, s18, v148
	v_add_u32_e32 v190, s19, v2
	s_lshl_b32 s18, s33, 14
	s_cmp_lg_u32 s73, -1
	s_cselect_b32 s33, s73, 0
	v_lshlrev_b32_e32 v2, 8, v35
	v_bitop3_b32 v4, v161, v36, 7 bitop3:0x78
	s_add_i32 s33, s33, s18
	v_lshlrev_b32_e32 v3, 4, v35
	v_lshl_or_b32 v193, v4, 4, v2
	v_and_b32_e32 v3, 0x70, v3
	v_add_u32_e32 v78, s33, v193
	v_or_b32_e32 v4, 32, v148
	ds_read_b128 v[46:49], v78 offset:0
	v_bitop3_b32 v194, v4, v2, v3 bitop3:0xde
	ds_read_b128 v[50:53], v78 offset:0x2000
	v_add_u32_e32 v79, s33, v194
	v_or_b32_e32 v4, 64, v148
	ds_read_b128 v[54:57], v79 offset:0
	v_bitop3_b32 v195, v4, v2, v3 bitop3:0xde
	ds_read_b128 v[58:61], v79 offset:0x2000
	v_add_u32_e32 v80, s33, v195
	v_or_b32_e32 v4, 0x60, v148
	ds_read_b128 v[62:65], v80 offset:0
	v_bitop3_b32 v196, v4, v2, v3 bitop3:0xde
	ds_read_b128 v[66:69], v80 offset:0x2000
	v_add_u32_e32 v81, s33, v196
	ds_read_b128 v[70:73], v81 offset:0
	ds_read_b128 v[74:77], v81 offset:0x2000
	ds_read_b128 v[18:21], v192
	ds_read_b128 v[22:25], v192 offset:32
	ds_read_b128 v[2:5], v192 offset:128
	ds_read_b128 v[6:9], v192 offset:160
	ds_read_b128 v[26:29], v192 offset:64
	ds_read_b128 v[30:33], v192 offset:96
	ds_read_b128 v[10:13], v192 offset:192
	ds_read_b128 v[14:17], v192 offset:224
	s_waitcnt lgkmcnt(12)
	s_cmp_gt_i32 s19, 62
	s_waitcnt lgkmcnt(0)
	v_mfma_f32_32x32x16_bf16 v[18:33], v[46:49], v[142:145], v[18:33]
	ds_read_b128 v[46:49], v78 offset:0x80
	v_mfma_f32_32x32x16_bf16 v[18:33], v[54:57], v[138:141], v[18:33]
	ds_read_b128 v[54:57], v79 offset:0x80
	v_mfma_f32_32x32x16_bf16 v[2:17], v[50:53], v[142:145], v[2:17]
	ds_read_b128 v[50:53], v78 offset:0x2080
	v_mfma_f32_32x32x16_bf16 v[2:17], v[58:61], v[138:141], v[2:17]
	ds_read_b128 v[58:61], v79 offset:0x2080
	s_waitcnt lgkmcnt(4)
	s_nop 0
	v_mfma_f32_32x32x16_bf16 v[18:33], v[62:65], v[134:137], v[18:33]
	ds_read_b128 v[62:65], v80 offset:0x80
	v_mfma_f32_32x32x16_bf16 v[18:33], v[70:73], v[130:133], v[18:33]
	ds_read_b128 v[70:73], v81 offset:0x80
	v_mfma_f32_32x32x16_bf16 v[2:17], v[66:69], v[134:137], v[2:17]
	ds_read_b128 v[66:69], v80 offset:0x2080
	v_mfma_f32_32x32x16_bf16 v[2:17], v[74:77], v[130:133], v[2:17]
	ds_read_b128 v[74:77], v81 offset:0x2080
	s_waitcnt lgkmcnt(4)
	s_nop 0
	s_waitcnt lgkmcnt(0)
	v_mfma_f32_32x32x16_bf16 v[18:33], v[46:49], v[126:129], v[18:33]
	v_mfma_f32_32x32x16_bf16 v[18:33], v[54:57], v[122:125], v[18:33]
	v_mfma_f32_32x32x16_bf16 v[18:33], v[62:65], v[118:121], v[18:33]
	v_mfma_f32_32x32x16_bf16 v[18:33], v[70:73], v[114:117], v[18:33]
	v_mfma_f32_32x32x16_bf16 v[2:17], v[50:53], v[126:129], v[2:17]
	v_mfma_f32_32x32x16_bf16 v[2:17], v[58:61], v[122:125], v[2:17]
	v_mfma_f32_32x32x16_bf16 v[2:17], v[66:69], v[118:121], v[2:17]
	v_mfma_f32_32x32x16_bf16 v[2:17], v[74:77], v[114:117], v[2:17]
	s_cbranch_scc1 .LBB0_977
	v_cmp_gt_u32_e32 vcc, s16, v190
	v_add_u32_e32 v46, 0xffffefe0, v190
	s_nop 7
	v_cndmask_b32_e32 v18, v240, v18, vcc
	v_cmp_lt_u32_e32 vcc, s54, v46
	v_add_u32_e32 v46, 0xffffefff, v190
	s_nop 0
	v_cndmask_b32_e32 v2, v240, v2, vcc
	v_cmp_lt_u32_e32 vcc, s54, v46
	v_add_u32_e32 v46, 0xffffefdf, v190
	s_nop 0
	v_cndmask_b32_e32 v19, v240, v19, vcc
	v_cmp_lt_u32_e32 vcc, s54, v46
	v_add_u32_e32 v46, 0xffffeffe, v190
	s_nop 0
	v_cndmask_b32_e32 v3, v240, v3, vcc
	v_cmp_lt_u32_e32 vcc, s54, v46
	v_add_u32_e32 v46, 0xffffefde, v190
	s_nop 0
	v_cndmask_b32_e32 v20, v240, v20, vcc
	v_cmp_lt_u32_e32 vcc, s54, v46
	v_add_u32_e32 v46, 0xffffeffd, v190
	s_nop 0
	v_cndmask_b32_e32 v4, v240, v4, vcc
	v_cmp_lt_u32_e32 vcc, s54, v46
	v_add_u32_e32 v46, 0xffffefdd, v190
	s_nop 0
	v_cndmask_b32_e32 v21, v240, v21, vcc
	v_cmp_lt_u32_e32 vcc, s54, v46
	v_add_u32_e32 v46, 0xffffeff8, v190
	s_nop 0
	v_cndmask_b32_e32 v5, v240, v5, vcc
	v_cmp_lt_u32_e32 vcc, s54, v46
	v_add_u32_e32 v46, 0xffffefd8, v190
	s_nop 0
	v_cndmask_b32_e32 v22, v240, v22, vcc
	v_cmp_lt_u32_e32 vcc, s54, v46
	v_add_u32_e32 v46, 0xffffeff7, v190
	s_nop 0
	v_cndmask_b32_e32 v6, v240, v6, vcc
	v_cmp_lt_u32_e32 vcc, s54, v46
	v_add_u32_e32 v46, 0xffffefd7, v190
	s_nop 0
	v_cndmask_b32_e32 v23, v240, v23, vcc
	v_cmp_lt_u32_e32 vcc, s54, v46
	v_add_u32_e32 v46, 0xffffeff6, v190
	s_nop 0
	v_cndmask_b32_e32 v7, v240, v7, vcc
	v_cmp_lt_u32_e32 vcc, s54, v46
	v_add_u32_e32 v46, 0xffffefd6, v190
	s_nop 0
	v_cndmask_b32_e32 v24, v240, v24, vcc
	v_cmp_lt_u32_e32 vcc, s54, v46
	v_add_u32_e32 v46, 0xffffeff5, v190
	s_nop 0
	v_cndmask_b32_e32 v8, v240, v8, vcc
	v_cmp_lt_u32_e32 vcc, s54, v46
	v_add_u32_e32 v46, 0xffffefd5, v190
	s_nop 0
	v_cndmask_b32_e32 v25, v240, v25, vcc
	v_cmp_lt_u32_e32 vcc, s54, v46
	v_add_u32_e32 v46, 0xffffeff0, v190
	s_nop 0
	v_cndmask_b32_e32 v9, v240, v9, vcc
	v_cmp_lt_u32_e32 vcc, s54, v46
	v_add_u32_e32 v46, 0xffffefd0, v190
	s_nop 0
	v_cndmask_b32_e32 v26, v240, v26, vcc
	v_cmp_lt_u32_e32 vcc, s54, v46
	v_add_u32_e32 v46, 0xffffefef, v190
	s_nop 0
	v_cndmask_b32_e32 v10, v240, v10, vcc
	v_cmp_lt_u32_e32 vcc, s54, v46
	v_add_u32_e32 v46, 0xffffefcf, v190
	s_nop 0
	v_cndmask_b32_e32 v27, v240, v27, vcc
	v_cmp_lt_u32_e32 vcc, s54, v46
	v_add_u32_e32 v46, 0xffffefee, v190
	s_nop 0
	v_cndmask_b32_e32 v11, v240, v11, vcc
	v_cmp_lt_u32_e32 vcc, s54, v46
	v_add_u32_e32 v46, 0xffffefce, v190
	s_nop 0
	v_cndmask_b32_e32 v28, v240, v28, vcc
	v_cmp_lt_u32_e32 vcc, s54, v46
	v_add_u32_e32 v46, 0xffffefed, v190
	s_nop 0
	v_cndmask_b32_e32 v12, v240, v12, vcc
	v_cmp_lt_u32_e32 vcc, s54, v46
	v_add_u32_e32 v46, 0xffffefcd, v190
	s_nop 0
	v_cndmask_b32_e32 v29, v240, v29, vcc
	v_cmp_lt_u32_e32 vcc, s54, v46
	v_add_u32_e32 v46, 0xffffefe8, v190
	s_nop 0
	v_cndmask_b32_e32 v13, v240, v13, vcc
	v_cmp_lt_u32_e32 vcc, s54, v46
	v_add_u32_e32 v46, 0xffffefc8, v190
	s_nop 0
	v_cndmask_b32_e32 v30, v240, v30, vcc
	v_cmp_lt_u32_e32 vcc, s54, v46
	v_add_u32_e32 v46, 0xffffefe7, v190
	s_nop 0
	v_cndmask_b32_e32 v14, v240, v14, vcc
	v_cmp_lt_u32_e32 vcc, s54, v46
	v_add_u32_e32 v46, 0xffffefc7, v190
	s_nop 0
	v_cndmask_b32_e32 v31, v240, v31, vcc
	v_cmp_lt_u32_e32 vcc, s54, v46
	v_add_u32_e32 v46, 0xffffefe6, v190
	s_nop 0
	v_cndmask_b32_e32 v15, v240, v15, vcc
	v_cmp_lt_u32_e32 vcc, s54, v46
	v_add_u32_e32 v46, 0xffffefc6, v190
	s_nop 0
	v_cndmask_b32_e32 v32, v240, v32, vcc
	v_cmp_lt_u32_e32 vcc, s54, v46
	v_add_u32_e32 v46, 0xffffefe5, v190
	s_nop 0
	v_cndmask_b32_e32 v16, v240, v16, vcc
	v_cmp_lt_u32_e32 vcc, s54, v46
	v_add_u32_e32 v46, 0xffffefc5, v190
	s_nop 0
	v_cndmask_b32_e32 v33, v240, v33, vcc
	v_cmp_lt_u32_e32 vcc, s54, v46
	s_nop 1
	v_cndmask_b32_e32 v17, v240, v17, vcc

; #define K_LD(R, A0, A1, off) do { KRD(R##0, A0, off); KRD(R##1, A0, off + 8192); KRD(R##2, A1, off); KRD(R##3, A1, off + 8192); } while (0)
; #define K_MM(R, d) do { p0 = __builtin_amdgcn_mfma_f32_32x32x16_bf16(R##0, qr[d + 0], p0, 0, 0, 0); p1 = __builtin_amdgcn_mfma_f32_32x32x16_bf16(R##1, qr[d + 0], p1, 0, 0, 0); \
;         p0 = __builtin_amdgcn_mfma_f32_32x32x16_bf16(R##2, qr[d + 1], p0, 0, 0, 0); p1 = __builtin_amdgcn_mfma_f32_32x32x16_bf16(R##3, qr[d + 1], p1, 0, 0, 0); } while (0)
; __device__ __forceinline__ void finishSM(f32x16& p0, f32x16& p1, float alpha, float& l_reg, bf16x8& pa0, bf16x8& pa1, bf16x8& pa2, bf16x8& pa3) {
;     for (int r = 0; r < 16; ++r) p1[r] = __builtin_amdgcn_exp2f(p1[r]);
;     typedef float f32x8_ __attribute__((ext_vector_type(8))); typedef float f32x2_ __attribute__((ext_vector_type(2)));
;     const f32x16 s16 = p0 + p1; const f32x8_ s8 = s16.lo + s16.hi; const f32x4 s4 = s8.lo + s8.hi; const f32x2_ s2 = s4.lo + s4.hi; float ps = s2.x + s2.y;
;     { auto rr = __builtin_amdgcn_permlane32_swap(__float_as_uint(ps), __float_as_uint(ps), false, false);
;       ps = __uint_as_float(rr[0]) + __uint_as_float(rr[1]); }
;     l_reg = l_reg * alpha + ps;
;     ...
;     PK4(p0, 0, pa0); PK4(p0, 8, pa1); PK4(p1, 0, pa2); PK4(p1, 8, pa3);
;     ...
; }
; template <bool SK>
; __device__ __forceinline__ void qkt_x(f32x16& p0, f32x16& p1, const char* K_lds, int r32, int hi, const bf16x8* qr, bool act, const char* fb) {
;     const int k0a = (int)(uintptr_t)K_lds + KSWZ(r32, (0 * 16 + hi * 8) * 2), k1a = (int)(uintptr_t)K_lds + KSWZ(r32, (1 * 16 + hi * 8) * 2), k2a = (int)(uintptr_t)K_lds + KSWZ(r32, (2 * 16 + hi * 8) * 2), k3a = (int)(uintptr_t)K_lds + KSWZ(r32, (3 * 16 + hi * 8) * 2);
;     ...
;     bf16x8 ka0, ka1, ka2, ka3, kb0, kb1, kb2, kb3;
;     K_LD(ka, k0a, k1a, 0); K_LD(kb, k2a, k3a, 0);
; #pragma unroll
;     for (int q = 0; q < 4; ++q) { const f32x4 b0 = *reinterpret_cast<const f32x4*>(fb + q * 32), b1 = *reinterpret_cast<const f32x4*>(fb + 128 + q * 32);
; #pragma unroll
;         for (int i = 0; i < 4; ++i) { p0[4 * q + i] = b0[i]; p1[4 * q + i] = b1[i]; } }
;     K_W(12, ka);
;     K_MM(ka, 0); K_LD(ka, k0a, k1a, 128);
;     K_W(4, kb); K_MM(kb, 2); K_LD(kb, k2a, k3a, 128);
;     K_W(4, ka); K_MM(ka, 4);
;     K_W(0, kb); K_MM(kb, 6);
.LBB0_982:
	s_add_i32 s0, s31, 1
	s_cmp_lg_u32 s31, 2
	s_cselect_b32 s44, s0, 0
	s_lshl_b32 s45, s44, 14
	v_lshl_add_u64 v[180:181], v[152:153], 0, s[68:69]
	s_add_i32 s0, s45, s24
	v_lshl_add_u64 v[82:83], v[180:181], 0, s[38:39]
	s_mov_b32 m0, s0
	v_lshl_add_u64 v[188:189], v[154:155], 0, s[68:69]
	global_load_lds_dwordx4 v[82:83], off
	v_lshl_add_u64 v[82:83], v[188:189], 0, s[38:39]
	s_add_i32 m0, s0, 0x400
	v_lshl_add_u64 v[158:159], v[150:151], 0, s[68:69]
	s_add_i32 s40, s45, s20
	global_load_lds_dwordx4 v[82:83], off
	v_lshl_add_u64 v[82:83], v[158:159], 0, s[38:39]
	s_mov_b32 m0, s40
	s_mov_b64 s[0:1], 0x8080
	global_load_lds_dwordx4 v[82:83], off
	v_lshl_add_u64 v[82:83], v[158:159], 0, s[0:1]
	s_add_i32 m0, s40, 0x400
	s_nop 0
	global_load_lds_dwordx4 v[82:83], off
	s_lshl_b32 s0, s31, 14
	s_cmp_lg_u32 s73, -1
	s_cselect_b32 s1, s73, 0
	s_add_i32 s1, s1, s0
	v_add_u32_e32 v67, s1, v193
	ds_read_b128 v[202:205], v67 offset:0
	ds_read_b128 v[206:209], v67 offset:0x2000
	v_add_u32_e32 v156, s1, v194
	ds_read_b128 v[210:213], v156 offset:0
	ds_read_b128 v[214:217], v156 offset:0x2000
	v_add_u32_e32 v157, s1, v195
	ds_read_b128 v[218:221], v157 offset:0
	ds_read_b128 v[222:225], v157 offset:0x2000
	v_add_u32_e32 v160, s1, v196
	ds_read_b128 v[226:229], v160 offset:0
	ds_read_b128 v[242:245], v160 offset:0x2000
	ds_read_b128 v[98:101], v198
	ds_read_b128 v[102:105], v198 offset:32
	ds_read_b128 v[82:85], v198 offset:128
	ds_read_b128 v[86:89], v198 offset:160
	ds_read_b128 v[106:109], v198 offset:64
	ds_read_b128 v[90:93], v198 offset:192
	ds_read_b128 v[110:113], v198 offset:96
	ds_read_b128 v[94:97], v198 offset:224
	s_waitcnt lgkmcnt(12)
	v_exp_f32_e32 v184, v66
	s_waitcnt lgkmcnt(0)
	v_mfma_f32_32x32x16_bf16 v[98:113], v[202:205], v[142:145], v[98:113]
	ds_read_b128 v[202:205], v67 offset:0x80
	v_exp_f32_e32 v185, v1
	v_exp_f32_e32 v186, v68
	v_exp_f32_e32 v187, v69
	s_nop 0
	v_pk_add_f32 v[68:69], v[176:177], v[186:187]
	v_mfma_f32_32x32x16_bf16 v[82:97], v[206:209], v[142:145], v[82:97]
	ds_read_b128 v[206:209], v67 offset:0x2080
	v_mfma_f32_32x32x16_bf16 v[98:113], v[210:213], v[138:141], v[98:113]
	ds_read_b128 v[210:213], v156 offset:0x80
	v_mfma_f32_32x32x16_bf16 v[82:97], v[214:217], v[138:141], v[82:97]
	ds_read_b128 v[214:217], v156 offset:0x2080
	s_waitcnt lgkmcnt(4)
	s_nop 0
	v_mfma_f32_32x32x16_bf16 v[98:113], v[218:221], v[134:137], v[98:113]
	ds_read_b128 v[218:221], v157 offset:0x80
	v_mfma_f32_32x32x16_bf16 v[98:113], v[226:229], v[130:133], v[98:113]
	ds_read_b128 v[226:229], v160 offset:0x80
	v_mfma_f32_32x32x16_bf16 v[82:97], v[222:225], v[134:137], v[82:97]
	ds_read_b128 v[222:225], v157 offset:0x2080
	v_mfma_f32_32x32x16_bf16 v[82:97], v[242:245], v[130:133], v[82:97]
	ds_read_b128 v[242:245], v160 offset:0x2080
	s_waitcnt lgkmcnt(4)
	s_nop 0
	s_waitcnt lgkmcnt(0)
	v_mfma_f32_32x32x16_bf16 v[98:113], v[202:205], v[126:129], v[98:113]
	v_exp_f32_e32 v202, v70
	v_exp_f32_e32 v203, v71
	v_exp_f32_e32 v204, v72
	v_exp_f32_e32 v205, v73
	s_nop 0
	v_pk_add_f32 v[72:73], v[172:173], v[204:205]
	v_mfma_f32_32x32x16_bf16 v[82:97], v[206:209], v[126:129], v[82:97]
	v_exp_f32_e32 v206, v74
	v_exp_f32_e32 v207, v75
	v_exp_f32_e32 v208, v76
	v_exp_f32_e32 v209, v77
	v_pk_add_f32 v[76:77], v[178:179], v[184:185]
	v_pk_add_f32 v[74:75], v[168:169], v[206:207]
	v_pk_add_f32 v[66:67], v[166:167], v[208:209]
	v_mfma_f32_32x32x16_bf16 v[98:113], v[210:213], v[122:125], v[98:113]
	v_exp_f32_e32 v210, v78
	v_exp_f32_e32 v211, v79
	v_exp_f32_e32 v212, v80
	v_exp_f32_e32 v213, v81
	v_pk_add_f32 v[80:81], v[174:175], v[202:203]
	v_pk_add_f32 v[78:79], v[164:165], v[210:211]
	v_pk_add_f32 v[74:75], v[76:77], v[74:75]
	v_mfma_f32_32x32x16_bf16 v[82:97], v[214:217], v[122:125], v[82:97]
	v_add_f32_e64 v70, v162, v212
	v_add_f32_e64 v71, v163, v213
	v_add_f32_e64 v78, v80, v78
	v_add_f32_e64 v79, v81, v79
	v_add_f32_e64 v70, v72, v70
	v_add_f32_e64 v71, v73, v71
	v_pk_add_f32 v[66:67], v[68:69], v[66:67]
	v_pk_add_f32 v[68:69], v[74:75], v[78:79]
	v_pk_add_f32 v[66:67], v[66:67], v[70:71]
	v_mfma_f32_32x32x16_bf16 v[98:113], v[218:221], v[118:121], v[98:113]
	v_add_f32_e64 v66, v68, v66
	v_add_f32_e64 v67, v69, v67
	v_add_f32_e64 v156, v66, v67
	v_add_f32_e64 v157, v67, v66
	v_cvt_pk_bf16_f32 v66, v178, v179
	v_cvt_pk_bf16_f32 v67, v176, v177
	v_cvt_pk_bf16_f32 v68, v174, v175
	v_cvt_pk_bf16_f32 v69, v172, v173
	v_mfma_f32_32x32x16_bf16 v[82:97], v[222:225], v[118:121], v[82:97]
	v_mov_b32_e32 v1, v156
	s_nop 1
	v_permlane32_swap_b32_e32 v156, v1
	v_cvt_pk_bf16_f32 v70, v168, v169
	v_cvt_pk_bf16_f32 v71, v166, v167
	v_cvt_pk_bf16_f32 v72, v164, v165
	v_cvt_pk_bf16_f32 v73, v162, v163
	v_mfma_f32_32x32x16_bf16 v[98:113], v[226:229], v[114:117], v[98:113]
	v_cvt_pk_bf16_f32 v74, v184, v185
	v_cvt_pk_bf16_f32 v75, v186, v187
	v_cvt_pk_bf16_f32 v76, v202, v203
	v_cvt_pk_bf16_f32 v77, v204, v205
	v_cvt_pk_bf16_f32 v78, v206, v207
	v_cvt_pk_bf16_f32 v79, v208, v209
	v_cvt_pk_bf16_f32 v80, v210, v211
	v_mfma_f32_32x32x16_bf16 v[82:97], v[242:245], v[114:117], v[82:97]
	v_cvt_pk_bf16_f32 v81, v212, v213
	v_permlane32_swap_b32_e32 v66, v68
	v_permlane32_swap_b32_e32 v67, v69
	v_permlane32_swap_b32_e32 v70, v72
	v_permlane32_swap_b32_e32 v71, v73
	v_permlane32_swap_b32_e32 v74, v76
	v_permlane32_swap_b32_e32 v75, v77
	v_permlane32_swap_b32_e32 v78, v80
	v_permlane32_swap_b32_e32 v79, v81
	s_addk_i32 s0, 0xc000
	s_cmp_lg_u32 s31, 0
	s_cselect_b32 s0, s0, 0x8000
	v_add_u32_e32 v157, s0, v171
	ds_read_b64_tr_b16 v[162:163], v157 offset:0
	ds_read_b64_tr_b16 v[164:165], v157 offset:0x800
	ds_read_b64_tr_b16 v[166:167], v157 offset:0x1000
	ds_read_b64_tr_b16 v[168:169], v157 offset:0x1800
	ds_read_b64_tr_b16 v[172:173], v157 offset:0x2000
	ds_read_b64_tr_b16 v[174:175], v157 offset:0x2800
	ds_read_b64_tr_b16 v[176:177], v157 offset:0x3000
	ds_read_b64_tr_b16 v[178:179], v157 offset:0x3800
	ds_read_b64_tr_b16 v[202:203], v157 offset:0x200
	ds_read_b64_tr_b16 v[204:205], v157 offset:0xa00
	ds_read_b64_tr_b16 v[206:207], v157 offset:0x1200
	ds_read_b64_tr_b16 v[208:209], v157 offset:0x1a00
	ds_read_b64_tr_b16 v[210:211], v157 offset:0x2200
	ds_read_b64_tr_b16 v[212:213], v157 offset:0x2a00
	ds_read_b64_tr_b16 v[214:215], v157 offset:0x3200
	ds_read_b64_tr_b16 v[216:217], v157 offset:0x3a00
	s_nop 0
	s_waitcnt lgkmcnt(8)
; #define PV_LD(R, d0) do { constexpr int b_ = v_rd_off(d0, 0, 0); TRRD(R##0, b_); TRRD(R##1, b_ + 2048); TRRD(R##2, b_ + 4096); TRRD(R##3, b_ + 6144); TRRD(R##4, b_ + 8192); TRRD(R##5, b_ + 10240); TRRD(R##6, b_ + 12288); TRRD(R##7, b_ + 14336); } while (0)
; #define PV_MM(R, d0) do { o[d0] = __builtin_amdgcn_mfma_f32_32x32x16_bf16(PV_J(R##0, R##1), pa0, o[d0], 0, 0, 0); o[d0] = __builtin_amdgcn_mfma_f32_32x32x16_bf16(PV_J(R##2, R##3), pa1, o[d0], 0, 0, 0); \
;         o[d0] = __builtin_amdgcn_mfma_f32_32x32x16_bf16(PV_J(R##4, R##5), pa2, o[d0], 0, 0, 0); o[d0] = __builtin_amdgcn_mfma_f32_32x32x16_bf16(PV_J(R##6, R##7), pa3, o[d0], 0, 0, 0); } while (0)
; #define PV_W(n, R) asm volatile("s_waitcnt lgkmcnt(" #n ")" : "+v"(R##0), "+v"(R##1), "+v"(R##2), "+v"(R##3), "+v"(R##4), "+v"(R##5), "+v"(R##6), "+v"(R##7) :: "memory")
; __device__ __forceinline__ void mask_tile(f32x16& p0, f32x16& p1, int dq, unsigned W) {
;     const float NEG = -__builtin_inff();
; #pragma unroll
;     for (int r = 0; r < 16; ++r) {
;         const int c = (r & 3) + 8 * (r >> 2);
;         if ((unsigned)(dq - c) >= W) p0[r] = NEG;
;         if ((unsigned)(dq - c - 32) >= W) p1[r] = NEG;
;     }
; }
; template <bool SK>
; __device__ __forceinline__ void pv_tile_x(f32x16* o, int vb, bf16x8 pa0, bf16x8 pa1, bf16x8 pa2, bf16x8 pa3, bool act) {
;     ...
;     s16x4 fa0, fa1, fa2, fa3, fa4, fa5, fa6, fa7, fb0, fb1, fb2, fb3, fb4, fb5, fb6, fb7;
;     PV_LD(fa, 0); PV_LD(fb, 1);
;     PV_W(8, fa); PV_MM(fa, 0); PV_LD(fa, 2);
;     PV_W(8, fb); PV_MM(fb, 1); PV_LD(fb, 3);
;     PV_W(8, fa); PV_MM(fa, 2);
;     PV_W(0, fb); PV_MM(fb, 3);
	s_sub_i32 s0, s35, 64
	v_mfma_f32_32x32x16_bf16 v[50:65], v[162:165], v[66:69], v[50:65]
	ds_read_b64_tr_b16 v[162:163], v157 offset:0x400
	ds_read_b64_tr_b16 v[164:165], v157 offset:0xc00
	s_cmp_le_i32 s0, s19
	v_mfma_f32_32x32x16_bf16 v[50:65], v[166:169], v[70:73], v[50:65]
	ds_read_b64_tr_b16 v[166:167], v157 offset:0x1400
	ds_read_b64_tr_b16 v[168:169], v157 offset:0x1c00
	v_mfma_f32_32x32x16_bf16 v[50:65], v[172:175], v[74:77], v[50:65]
	ds_read_b64_tr_b16 v[172:173], v157 offset:0x2400
	ds_read_b64_tr_b16 v[174:175], v157 offset:0x2c00
	v_mfma_f32_32x32x16_bf16 v[50:65], v[176:179], v[78:81], v[50:65]
	ds_read_b64_tr_b16 v[176:177], v157 offset:0x3400
	ds_read_b64_tr_b16 v[178:179], v157 offset:0x3c00
	s_waitcnt lgkmcnt(8)
	s_nop 0
	v_mfma_f32_32x32x16_bf16 v[34:49], v[202:205], v[66:69], v[34:49]
	ds_read_b64_tr_b16 v[202:203], v157 offset:0x600
	ds_read_b64_tr_b16 v[204:205], v157 offset:0xe00
	v_mfma_f32_32x32x16_bf16 v[34:49], v[206:209], v[70:73], v[34:49]
	ds_read_b64_tr_b16 v[206:207], v157 offset:0x1600
	ds_read_b64_tr_b16 v[208:209], v157 offset:0x1e00
	v_mfma_f32_32x32x16_bf16 v[34:49], v[210:213], v[74:77], v[34:49]
	ds_read_b64_tr_b16 v[210:211], v157 offset:0x2600
	ds_read_b64_tr_b16 v[212:213], v157 offset:0x2e00
	v_mfma_f32_32x32x16_bf16 v[34:49], v[214:217], v[78:81], v[34:49]
	ds_read_b64_tr_b16 v[214:215], v157 offset:0x3600
	ds_read_b64_tr_b16 v[216:217], v157 offset:0x3e00
	s_waitcnt lgkmcnt(8)
	s_nop 0
	s_waitcnt lgkmcnt(0)
	v_mfma_f32_32x32x16_bf16 v[18:33], v[162:165], v[66:69], v[18:33]
	v_mfma_f32_32x32x16_bf16 v[18:33], v[166:169], v[70:73], v[18:33]
	v_mfma_f32_32x32x16_bf16 v[18:33], v[172:175], v[74:77], v[18:33]
	v_mfma_f32_32x32x16_bf16 v[18:33], v[176:179], v[78:81], v[18:33]
	v_mfma_f32_32x32x16_bf16 v[2:17], v[202:205], v[66:69], v[2:17]
	v_mfma_f32_32x32x16_bf16 v[2:17], v[206:209], v[70:73], v[2:17]
	v_mfma_f32_32x32x16_bf16 v[2:17], v[210:213], v[74:77], v[2:17]
	v_mfma_f32_32x32x16_bf16 v[2:17], v[214:217], v[78:81], v[2:17]
	s_cbranch_scc1 .LBB0_984
	v_add_u32_e32 v66, 0x107b, v199
	v_cmp_gt_u32_e32 vcc, s16, v66
	v_add_u32_e32 v66, 0x5b, v199
	s_nop 0
	v_cndmask_b32_e32 v98, v240, v98, vcc
	v_cmp_lt_u32_e32 vcc, s54, v66
	v_add_u32_e32 v66, 0x7a, v199
	s_nop 0
	v_cndmask_b32_e32 v82, v240, v82, vcc
	v_cmp_lt_u32_e32 vcc, s54, v66
	v_add_u32_e32 v66, 0x5a, v199
	s_nop 0
	v_cndmask_b32_e32 v99, v240, v99, vcc
	v_cmp_lt_u32_e32 vcc, s54, v66
	v_add_u32_e32 v66, 0x79, v199
	s_nop 0
	v_cndmask_b32_e32 v83, v240, v83, vcc
	v_cmp_lt_u32_e32 vcc, s54, v66
	v_add_u32_e32 v66, 0x59, v199
	s_nop 0
	v_cndmask_b32_e32 v100, v240, v100, vcc
	v_cmp_lt_u32_e32 vcc, s54, v66
	v_add_u32_e32 v66, 0x78, v199
	s_nop 0
	v_cndmask_b32_e32 v84, v240, v84, vcc
	v_cmp_lt_u32_e32 vcc, s54, v66
	v_add_u32_e32 v66, 0x58, v199
	s_nop 0
	v_cndmask_b32_e32 v101, v240, v101, vcc
	v_cmp_lt_u32_e32 vcc, s54, v66
	v_add_u32_e32 v66, 0x73, v199
	s_nop 0
	v_cndmask_b32_e32 v85, v240, v85, vcc
	v_cmp_lt_u32_e32 vcc, s54, v66
	v_add_u32_e32 v66, 0x53, v199
	s_nop 0
	v_cndmask_b32_e32 v102, v240, v102, vcc
	v_cmp_lt_u32_e32 vcc, s54, v66
	v_add_u32_e32 v66, 0x72, v199
	s_nop 0
	v_cndmask_b32_e32 v86, v240, v86, vcc
	v_cmp_lt_u32_e32 vcc, s54, v66
	v_add_u32_e32 v66, 0x52, v199
	s_nop 0
	v_cndmask_b32_e32 v103, v240, v103, vcc
	v_cmp_lt_u32_e32 vcc, s54, v66
	v_add_u32_e32 v66, 0x71, v199
	s_nop 0
	v_cndmask_b32_e32 v87, v240, v87, vcc
	v_cmp_lt_u32_e32 vcc, s54, v66
	v_add_u32_e32 v66, 0x51, v199
	s_nop 0
	v_cndmask_b32_e32 v104, v240, v104, vcc
	v_cmp_lt_u32_e32 vcc, s54, v66
	v_add_u32_e32 v66, 0x70, v199
	s_nop 0
	v_cndmask_b32_e32 v88, v240, v88, vcc
	v_cmp_lt_u32_e32 vcc, s54, v66
	v_add_u32_e32 v66, 0x50, v199
	s_nop 0
	v_cndmask_b32_e32 v105, v240, v105, vcc
	v_cmp_lt_u32_e32 vcc, s54, v66
	v_add_u32_e32 v66, 0x6b, v199
	s_nop 0
	v_cndmask_b32_e32 v89, v240, v89, vcc
	v_cmp_lt_u32_e32 vcc, s54, v66
	v_add_u32_e32 v66, 0x4b, v199
	s_nop 0
	v_cndmask_b32_e32 v106, v240, v106, vcc
	v_cmp_lt_u32_e32 vcc, s54, v66
	v_add_u32_e32 v66, 0x6a, v199
	s_nop 0
	v_cndmask_b32_e32 v90, v240, v90, vcc
	v_cmp_lt_u32_e32 vcc, s54, v66
	v_add_u32_e32 v66, 0x4a, v199
	s_nop 0
	v_cndmask_b32_e32 v107, v240, v107, vcc
	v_cmp_lt_u32_e32 vcc, s54, v66
	v_add_u32_e32 v66, 0x69, v199
	s_nop 0
	v_cndmask_b32_e32 v91, v240, v91, vcc
	v_cmp_lt_u32_e32 vcc, s54, v66
	v_add_u32_e32 v66, 0x49, v199
	s_nop 0
	v_cndmask_b32_e32 v108, v240, v108, vcc
	v_cmp_lt_u32_e32 vcc, s54, v66
	v_add_u32_e32 v66, 0x68, v199
	s_nop 0
	v_cndmask_b32_e32 v92, v240, v92, vcc
	v_cmp_lt_u32_e32 vcc, s54, v66
	v_add_u32_e32 v66, 0x48, v199
	s_nop 0
	v_cndmask_b32_e32 v109, v240, v109, vcc
	v_cmp_lt_u32_e32 vcc, s54, v66
	v_add_u32_e32 v66, 0x63, v199
	s_nop 0
	v_cndmask_b32_e32 v93, v240, v93, vcc
	v_cmp_lt_u32_e32 vcc, s54, v66
	v_add_u32_e32 v66, 0x43, v199
	s_nop 0
	v_cndmask_b32_e32 v110, v240, v110, vcc
	v_cmp_lt_u32_e32 vcc, s54, v66
	v_add_u32_e32 v66, 0x62, v199
	s_nop 0
	v_cndmask_b32_e32 v94, v240, v94, vcc
	v_cmp_lt_u32_e32 vcc, s54, v66
	v_add_u32_e32 v66, 0x42, v199
	s_nop 0
	v_cndmask_b32_e32 v111, v240, v111, vcc
	v_cmp_lt_u32_e32 vcc, s54, v66
	v_add_u32_e32 v66, 0x61, v199
	s_nop 0
	v_cndmask_b32_e32 v95, v240, v95, vcc
	v_cmp_lt_u32_e32 vcc, s54, v66
	v_add_u32_e32 v66, 0x41, v199
	s_nop 0
	v_cndmask_b32_e32 v112, v240, v112, vcc
	v_cmp_lt_u32_e32 vcc, s54, v66
	v_add_u32_e32 v66, 0x60, v199
	s_nop 0
	v_cndmask_b32_e32 v96, v240, v96, vcc
	v_cmp_lt_u32_e32 vcc, s54, v66
	v_add_u32_e32 v66, 64, v199
	s_nop 0
	v_cndmask_b32_e32 v113, v240, v113, vcc
	v_cmp_lt_u32_e32 vcc, s54, v66
	s_nop 1
	v_cndmask_b32_e32 v97, v240, v97, vcc

; __device__ __forceinline__ void partialSM(f32x16& p0, f32x16& p1, float& m_reg, float& mn, float& alpha) {
;     float pmax = p0[0]; for (int r = 1; r < 16; ++r) pmax = fmaxf(pmax, p0[r]); for (int r = 0; r < 16; ++r) pmax = fmaxf(pmax, p1[r]);
;     { auto rr = __builtin_amdgcn_permlane32_swap(__float_as_uint(pmax), __float_as_uint(pmax), false, false);
;       pmax = fmaxf(__uint_as_float(rr[0]), __uint_as_float(rr[1])); }
;     constexpr float THR2 = THR * 1.4426950408889634f;
;     if (__builtin_expect(__all((pmax - m_reg) <= THR2), 1)) { mn = m_reg; alpha = 1.f; }
;     else { mn = fmaxf(m_reg, pmax); alpha = __builtin_amdgcn_exp2f(m_reg - mn); m_reg = mn; }
;     p0 = p0 - mn; p1 = p1 - mn;
;     for (int r = 0; r < 16; ++r) p0[r] = __builtin_amdgcn_exp2f(p0[r]);
; }
; __device__ __forceinline__ void finishSM(f32x16& p0, f32x16& p1, float alpha, float& l_reg, bf16x8& pa0, bf16x8& pa1, bf16x8& pa2, bf16x8& pa3) {
;     for (int r = 0; r < 16; ++r) p1[r] = __builtin_amdgcn_exp2f(p1[r]);
;     typedef float f32x8_ __attribute__((ext_vector_type(8))); typedef float f32x2_ __attribute__((ext_vector_type(2)));
;     const f32x16 s16 = p0 + p1; const f32x8_ s8 = s16.lo + s16.hi; const f32x4 s4 = s8.lo + s8.hi; const f32x2_ s2 = s4.lo + s4.hi; float ps = s2.x + s2.y;
;     { auto rr = __builtin_amdgcn_permlane32_swap(__float_as_uint(ps), __float_as_uint(ps), false, false);
;       ps = __uint_as_float(rr[0]) + __uint_as_float(rr[1]); }
;     l_reg = l_reg * alpha + ps;
;     ...
;     PK4(p0, 0, pa0); PK4(p0, 8, pa1); PK4(p1, 0, pa2); PK4(p1, 8, pa3);
;     ...
; }
; template <bool SK>
; __device__ __forceinline__ void qkt_x(f32x16& p0, f32x16& p1, const char* K_lds, int r32, int hi, const bf16x8* qr, bool act, const char* fb) {
;     const int k0a = (int)(uintptr_t)K_lds + KSWZ(r32, (0 * 16 + hi * 8) * 2), k1a = (int)(uintptr_t)K_lds + KSWZ(r32, (1 * 16 + hi * 8) * 2), k2a = (int)(uintptr_t)K_lds + KSWZ(r32, (2 * 16 + hi * 8) * 2), k3a = (int)(uintptr_t)K_lds + KSWZ(r32, (3 * 16 + hi * 8) * 2);
;     ...
;     bf16x8 ka0, ka1, ka2, ka3, kb0, kb1, kb2, kb3;
;     K_LD(ka, k0a, k1a, 0); K_LD(kb, k2a, k3a, 0);
; #pragma unroll
;     for (int q = 0; q < 4; ++q) { const f32x4 b0 = *reinterpret_cast<const f32x4*>(fb + q * 32), b1 = *reinterpret_cast<const f32x4*>(fb + 128 + q * 32);
; #pragma unroll
;         for (int i = 0; i < 4; ++i) { p0[4 * q + i] = b0[i]; p1[4 * q + i] = b1[i]; } }
.LBB0_991:
	v_sub_f32_e32 v66, v113, v200
	v_sub_f32_e32 v67, v112, v200
	v_sub_f32_e32 v68, v111, v200
	v_sub_f32_e32 v69, v110, v200
	v_sub_f32_e32 v70, v109, v200
	v_sub_f32_e32 v71, v108, v200
	v_sub_f32_e32 v72, v107, v200
	v_sub_f32_e32 v73, v106, v200
	v_sub_f32_e32 v74, v105, v200
	v_sub_f32_e32 v75, v104, v200
	v_sub_f32_e32 v76, v103, v200
	v_sub_f32_e32 v77, v102, v200
	v_sub_f32_e32 v78, v101, v200
	v_sub_f32_e32 v79, v100, v200
	v_sub_f32_e32 v80, v99, v200
	v_sub_f32_e32 v81, v98, v200
	v_sub_f32_e32 v98, v97, v200
	v_sub_f32_e32 v99, v96, v200
	v_sub_f32_e32 v180, v95, v200
	v_sub_f32_e32 v181, v94, v200
	v_sub_f32_e32 v184, v93, v200
	v_sub_f32_e32 v185, v92, v200
	v_sub_f32_e32 v186, v91, v200
	v_sub_f32_e32 v187, v90, v200
	v_sub_f32_e32 v188, v89, v200
	v_sub_f32_e32 v189, v88, v200
	v_sub_f32_e32 v201, v87, v200
	v_sub_f32_e32 v218, v86, v200
	v_sub_f32_e32 v219, v85, v200
	v_exp_f32_e32 v110, v81
	v_exp_f32_e32 v111, v80
	v_exp_f32_e32 v112, v79
	v_exp_f32_e32 v113, v78
	v_exp_f32_e32 v158, v77
	v_exp_f32_e32 v159, v76
	v_exp_f32_e32 v108, v75
	v_exp_f32_e32 v109, v74
	v_exp_f32_e32 v104, v73
	v_exp_f32_e32 v105, v72
	v_exp_f32_e32 v106, v71
	v_exp_f32_e32 v107, v70
	v_exp_f32_e32 v100, v69
	v_exp_f32_e32 v101, v68
	v_exp_f32_e32 v102, v67
	v_exp_f32_e32 v103, v66
	v_sub_f32_e32 v220, v84, v200
	v_sub_f32_e32 v221, v83, v200
	v_sub_f32_e32 v222, v82, v200
	s_cmp_lg_u32 s73, -1
	s_cselect_b32 s0, s73, 0
	s_add_i32 s0, s0, s45
	v_add_u32_e32 v223, s0, v193
	ds_read_b128 v[162:165], v223 offset:0
	ds_read_b128 v[166:169], v223 offset:0x2000
	v_add_u32_e32 v224, s0, v194
	ds_read_b128 v[172:175], v224 offset:0
	ds_read_b128 v[176:179], v224 offset:0x2000
	v_add_u32_e32 v225, s0, v195
	ds_read_b128 v[202:205], v225 offset:0
	ds_read_b128 v[206:209], v225 offset:0x2000
	v_add_u32_e32 v226, s0, v196
	ds_read_b128 v[210:213], v226 offset:0
	ds_read_b128 v[214:217], v226 offset:0x2000
	ds_read_b128 v[82:85], v198 offset:256
	ds_read_b128 v[86:89], v198 offset:288
	ds_read_b128 v[66:69], v198 offset:384
	ds_read_b128 v[70:73], v198 offset:416
	ds_read_b128 v[90:93], v198 offset:320
	ds_read_b128 v[74:77], v198 offset:448
	ds_read_b128 v[94:97], v198 offset:352
	ds_read_b128 v[78:81], v198 offset:480
	s_waitcnt lgkmcnt(12)
	s_waitcnt lgkmcnt(0)
	v_mfma_f32_32x32x16_bf16 v[82:97], v[162:165], v[142:145], v[82:97]
	ds_read_b128 v[162:165], v223 offset:0x80
	v_mfma_f32_32x32x16_bf16 v[82:97], v[172:175], v[138:141], v[82:97]
	ds_read_b128 v[172:175], v224 offset:0x80
	v_mfma_f32_32x32x16_bf16 v[66:81], v[166:169], v[142:145], v[66:81]
	ds_read_b128 v[166:169], v223 offset:0x2080
	v_mfma_f32_32x32x16_bf16 v[66:81], v[176:179], v[138:141], v[66:81]
	ds_read_b128 v[176:179], v224 offset:0x2080
	s_waitcnt lgkmcnt(4)
	s_nop 0
	v_mfma_f32_32x32x16_bf16 v[82:97], v[202:205], v[134:137], v[82:97]
	ds_read_b128 v[202:205], v225 offset:0x80
	v_mfma_f32_32x32x16_bf16 v[82:97], v[210:213], v[130:133], v[82:97]
	ds_read_b128 v[210:213], v226 offset:0x80
	v_mfma_f32_32x32x16_bf16 v[66:81], v[206:209], v[134:137], v[66:81]
	ds_read_b128 v[206:209], v225 offset:0x2080
	v_mfma_f32_32x32x16_bf16 v[66:81], v[214:217], v[130:133], v[66:81]
	ds_read_b128 v[214:217], v226 offset:0x2080
	s_waitcnt lgkmcnt(4)
	s_nop 0
	s_waitcnt lgkmcnt(0)
	v_mfma_f32_32x32x16_bf16 v[82:97], v[162:165], v[126:129], v[82:97]
	v_exp_f32_e32 v162, v222
	v_exp_f32_e32 v163, v221
	v_exp_f32_e32 v164, v220
	v_exp_f32_e32 v165, v219
	v_mfma_f32_32x32x16_bf16 v[66:81], v[166:169], v[126:129], v[66:81]
	v_exp_f32_e32 v166, v218
	v_exp_f32_e32 v167, v201
	v_exp_f32_e32 v168, v189
	v_exp_f32_e32 v169, v188
	v_mfma_f32_32x32x16_bf16 v[82:97], v[172:175], v[122:125], v[82:97]
	v_exp_f32_e32 v172, v187
	v_exp_f32_e32 v173, v186
	v_exp_f32_e32 v174, v185
	v_exp_f32_e32 v175, v184
	v_pk_add_f32 v[186:187], v[168:169], v[108:109]
	v_pk_add_f32 v[188:189], v[172:173], v[104:105]
	v_mfma_f32_32x32x16_bf16 v[66:81], v[176:179], v[122:125], v[66:81]
	v_exp_f32_e32 v176, v181
	v_exp_f32_e32 v177, v180
	v_exp_f32_e32 v178, v99
	v_exp_f32_e32 v179, v98
	v_pk_add_f32 v[98:99], v[174:175], v[106:107]
	v_pk_add_f32 v[180:181], v[164:165], v[112:113]
	v_pk_add_f32 v[184:185], v[178:179], v[102:103]
	v_mfma_f32_32x32x16_bf16 v[82:97], v[202:205], v[118:121], v[82:97]
	v_add_f32_e64 v202, v162, v110
	v_add_f32_e64 v203, v163, v111
	v_add_f32_e64 v204, v176, v100
	v_add_f32_e64 v205, v177, v101
	v_add_f32_e64 v188, v202, v188
	v_add_f32_e64 v189, v203, v189
	v_pk_add_f32 v[184:185], v[186:187], v[184:185]
	v_pk_add_f32 v[98:99], v[180:181], v[98:99]
	v_cvt_pk_bf16_f32 v110, v110, v111
	v_cvt_pk_bf16_f32 v111, v112, v113
	v_mfma_f32_32x32x16_bf16 v[66:81], v[206:209], v[118:121], v[66:81]
	v_add_f32_e64 v206, v166, v158
	v_add_f32_e64 v207, v167, v159
	v_add_f32_e64 v98, v98, v184
	v_add_f32_e64 v99, v99, v185
	v_add_f32_e64 v204, v206, v204
	v_add_f32_e64 v205, v207, v205
	v_cvt_pk_bf16_f32 v112, v158, v159
	v_cvt_pk_bf16_f32 v113, v108, v109
	v_cvt_pk_bf16_f32 v104, v104, v105
	v_cvt_pk_bf16_f32 v105, v106, v107
	v_mfma_f32_32x32x16_bf16 v[82:97], v[210:213], v[114:117], v[82:97]
	v_add_f32_e64 v180, v188, v204
	v_add_f32_e64 v181, v189, v205
	v_cvt_pk_bf16_f32 v106, v100, v101
	v_cvt_pk_bf16_f32 v107, v102, v103
	v_cvt_pk_bf16_f32 v100, v162, v163
	v_cvt_pk_bf16_f32 v101, v164, v165
	v_cvt_pk_bf16_f32 v102, v166, v167
	v_add_f32_e64 v98, v180, v98
	v_add_f32_e64 v99, v181, v99
	v_mfma_f32_32x32x16_bf16 v[66:81], v[214:217], v[114:117], v[66:81]
	v_pk_add_f32 v[98:99], v[98:99], v[98:99] op_sel:[0,1] op_sel_hi:[1,0]
	v_cvt_pk_bf16_f32 v103, v168, v169
	v_cvt_pk_bf16_f32 v162, v172, v173
; #define PV_LD(R, d0) do { constexpr int b_ = v_rd_off(d0, 0, 0); TRRD(R##0, b_); TRRD(R##1, b_ + 2048); TRRD(R##2, b_ + 4096); TRRD(R##3, b_ + 6144); TRRD(R##4, b_ + 8192); TRRD(R##5, b_ + 10240); TRRD(R##6, b_ + 12288); TRRD(R##7, b_ + 14336); } while (0)
; #define PV_MM(R, d0) do { o[d0] = __builtin_amdgcn_mfma_f32_32x32x16_bf16(PV_J(R##0, R##1), pa0, o[d0], 0, 0, 0); o[d0] = __builtin_amdgcn_mfma_f32_32x32x16_bf16(PV_J(R##2, R##3), pa1, o[d0], 0, 0, 0); \
;         o[d0] = __builtin_amdgcn_mfma_f32_32x32x16_bf16(PV_J(R##4, R##5), pa2, o[d0], 0, 0, 0); o[d0] = __builtin_amdgcn_mfma_f32_32x32x16_bf16(PV_J(R##6, R##7), pa3, o[d0], 0, 0, 0); } while (0)
; #define PV_W(n, R) asm volatile("s_waitcnt lgkmcnt(" #n ")" : "+v"(R##0), "+v"(R##1), "+v"(R##2), "+v"(R##3), "+v"(R##4), "+v"(R##5), "+v"(R##6), "+v"(R##7) :: "memory")
; __device__ __forceinline__ void mask_tile(f32x16& p0, f32x16& p1, int dq, unsigned W) {
;     const float NEG = -__builtin_inff();
; #pragma unroll
;     for (int r = 0; r < 16; ++r) {
;         const int c = (r & 3) + 8 * (r >> 2);
;         if ((unsigned)(dq - c) >= W) p0[r] = NEG;
;         if ((unsigned)(dq - c - 32) >= W) p1[r] = NEG;
;     }
; }
; template <bool SK>
; __device__ __forceinline__ void pv_tile_x(f32x16* o, int vb, bf16x8 pa0, bf16x8 pa1, bf16x8 pa2, bf16x8 pa3, bool act) {
;     if (SK && !act) return;
;     ...
;     s16x4 fa0, fa1, fa2, fa3, fa4, fa5, fa6, fa7, fb0, fb1, fb2, fb3, fb4, fb5, fb6, fb7;
;     PV_LD(fa, 0); PV_LD(fb, 1);
;     PV_W(8, fa); PV_MM(fa, 0); PV_LD(fa, 2);
;     PV_W(8, fb); PV_MM(fb, 1); PV_LD(fb, 3);
;     PV_W(8, fa); PV_MM(fa, 2);
;     PV_W(0, fb); PV_MM(fb, 3);
	v_cvt_pk_bf16_f32 v163, v174, v175
	v_cvt_pk_bf16_f32 v164, v176, v177
	v_cvt_pk_bf16_f32 v165, v178, v179
	s_nop 0
	v_mov_b32_e32 v99, v98
	s_nop 1
	v_permlane32_swap_b32_e32 v98, v99
	v_permlane32_swap_b32_e32 v110, v112
	v_permlane32_swap_b32_e32 v111, v113
	v_permlane32_swap_b32_e32 v104, v106
	v_permlane32_swap_b32_e32 v105, v107
	v_permlane32_swap_b32_e32 v100, v102
	v_permlane32_swap_b32_e32 v101, v103
	v_permlane32_swap_b32_e32 v162, v164
	v_permlane32_swap_b32_e32 v163, v165
	s_addk_i32 s45, 0xc000
	s_cmp_lg_u32 s44, 0
	s_cselect_b32 s0, s45, 0x8000
	v_add_u32_e32 v108, s0, v171
	ds_read_b64_tr_b16 v[166:167], v108 offset:0
	ds_read_b64_tr_b16 v[168:169], v108 offset:0x800
	ds_read_b64_tr_b16 v[172:173], v108 offset:0x1000
	ds_read_b64_tr_b16 v[174:175], v108 offset:0x1800
	ds_read_b64_tr_b16 v[176:177], v108 offset:0x2000
	ds_read_b64_tr_b16 v[178:179], v108 offset:0x2800
	ds_read_b64_tr_b16 v[202:203], v108 offset:0x3000
	ds_read_b64_tr_b16 v[204:205], v108 offset:0x3800
	ds_read_b64_tr_b16 v[206:207], v108 offset:0x200
	ds_read_b64_tr_b16 v[208:209], v108 offset:0xa00
	ds_read_b64_tr_b16 v[210:211], v108 offset:0x1200
	ds_read_b64_tr_b16 v[212:213], v108 offset:0x1a00
	ds_read_b64_tr_b16 v[214:215], v108 offset:0x2200
	ds_read_b64_tr_b16 v[216:217], v108 offset:0x2a00
	ds_read_b64_tr_b16 v[218:219], v108 offset:0x3200
	ds_read_b64_tr_b16 v[220:221], v108 offset:0x3a00
	s_nop 0
	s_waitcnt lgkmcnt(8)
	s_cmp_le_i32 s35, s19
	v_mfma_f32_32x32x16_bf16 v[50:65], v[166:169], v[110:113], v[50:65]
	ds_read_b64_tr_b16 v[166:167], v108 offset:0x400
	ds_read_b64_tr_b16 v[168:169], v108 offset:0xc00
	v_mfma_f32_32x32x16_bf16 v[50:65], v[172:175], v[104:107], v[50:65]
	ds_read_b64_tr_b16 v[172:173], v108 offset:0x1400
	ds_read_b64_tr_b16 v[174:175], v108 offset:0x1c00
	v_mfma_f32_32x32x16_bf16 v[50:65], v[176:179], v[100:103], v[50:65]
	ds_read_b64_tr_b16 v[176:177], v108 offset:0x2400
	ds_read_b64_tr_b16 v[178:179], v108 offset:0x2c00
	v_mfma_f32_32x32x16_bf16 v[50:65], v[202:205], v[162:165], v[50:65]
	ds_read_b64_tr_b16 v[202:203], v108 offset:0x3400
	ds_read_b64_tr_b16 v[204:205], v108 offset:0x3c00
	s_waitcnt lgkmcnt(8)
	s_nop 0
	v_mfma_f32_32x32x16_bf16 v[34:49], v[206:209], v[110:113], v[34:49]
	ds_read_b64_tr_b16 v[206:207], v108 offset:0x600
	ds_read_b64_tr_b16 v[208:209], v108 offset:0xe00
	v_mfma_f32_32x32x16_bf16 v[34:49], v[210:213], v[104:107], v[34:49]
	ds_read_b64_tr_b16 v[210:211], v108 offset:0x1600
	ds_read_b64_tr_b16 v[212:213], v108 offset:0x1e00
	v_mfma_f32_32x32x16_bf16 v[34:49], v[214:217], v[100:103], v[34:49]
	ds_read_b64_tr_b16 v[214:215], v108 offset:0x2600
	ds_read_b64_tr_b16 v[216:217], v108 offset:0x2e00
	v_mfma_f32_32x32x16_bf16 v[34:49], v[218:221], v[162:165], v[34:49]
	ds_read_b64_tr_b16 v[218:219], v108 offset:0x3600
	ds_read_b64_tr_b16 v[220:221], v108 offset:0x3e00
	s_waitcnt lgkmcnt(8)
	s_nop 0
	s_waitcnt lgkmcnt(0)
	v_mfma_f32_32x32x16_bf16 v[18:33], v[166:169], v[110:113], v[18:33]
	v_mfma_f32_32x32x16_bf16 v[18:33], v[172:175], v[104:107], v[18:33]
	v_mfma_f32_32x32x16_bf16 v[18:33], v[176:179], v[100:103], v[18:33]
	v_mfma_f32_32x32x16_bf16 v[18:33], v[202:205], v[162:165], v[18:33]
	v_mfma_f32_32x32x16_bf16 v[2:17], v[206:209], v[110:113], v[2:17]
	v_mfma_f32_32x32x16_bf16 v[2:17], v[210:213], v[104:107], v[2:17]
	v_mfma_f32_32x32x16_bf16 v[2:17], v[214:217], v[100:103], v[2:17]
	v_mfma_f32_32x32x16_bf16 v[2:17], v[218:221], v[162:165], v[2:17]
	s_cbranch_scc1 .LBB0_993
	v_add_u32_e32 v100, 0x103b, v199
	v_cmp_gt_u32_e32 vcc, s16, v100
	v_add_u32_e32 v100, 27, v199
	s_nop 0
	v_cndmask_b32_e32 v82, v240, v82, vcc
	v_cmp_lt_u32_e32 vcc, s54, v100
	v_add_u32_e32 v100, 58, v199
	s_nop 0
	v_cndmask_b32_e32 v66, v240, v66, vcc
	v_cmp_lt_u32_e32 vcc, s54, v100
	v_add_u32_e32 v100, 26, v199
	s_nop 0
	v_cndmask_b32_e32 v83, v240, v83, vcc
	v_cmp_lt_u32_e32 vcc, s54, v100
	v_add_u32_e32 v100, 57, v199
	s_nop 0
	v_cndmask_b32_e32 v67, v240, v67, vcc
	v_cmp_lt_u32_e32 vcc, s54, v100
	v_add_u32_e32 v100, 25, v199
	s_nop 0
	v_cndmask_b32_e32 v84, v240, v84, vcc
	v_cmp_lt_u32_e32 vcc, s54, v100
	v_add_u32_e32 v100, 56, v199
	s_nop 0
	v_cndmask_b32_e32 v68, v240, v68, vcc
	v_cmp_lt_u32_e32 vcc, s54, v100
	v_add_u32_e32 v100, 24, v199
	s_nop 0
	v_cndmask_b32_e32 v85, v240, v85, vcc
	v_cmp_lt_u32_e32 vcc, s54, v100
	v_add_u32_e32 v100, 51, v199
	s_nop 0
	v_cndmask_b32_e32 v69, v240, v69, vcc
	v_cmp_lt_u32_e32 vcc, s54, v100
	v_add_u32_e32 v100, 19, v199
	s_nop 0
	v_cndmask_b32_e32 v86, v240, v86, vcc
	v_cmp_lt_u32_e32 vcc, s54, v100
	v_add_u32_e32 v100, 50, v199
	s_nop 0
	v_cndmask_b32_e32 v70, v240, v70, vcc
	v_cmp_lt_u32_e32 vcc, s54, v100
	v_add_u32_e32 v100, 18, v199
	s_nop 0
	v_cndmask_b32_e32 v87, v240, v87, vcc
	v_cmp_lt_u32_e32 vcc, s54, v100
	v_add_u32_e32 v100, 49, v199
	s_nop 0
	v_cndmask_b32_e32 v71, v240, v71, vcc
	v_cmp_lt_u32_e32 vcc, s54, v100
	v_add_u32_e32 v100, 17, v199
	s_nop 0
	v_cndmask_b32_e32 v88, v240, v88, vcc
	v_cmp_lt_u32_e32 vcc, s54, v100
	v_add_u32_e32 v100, 48, v199
	s_nop 0
	v_cndmask_b32_e32 v72, v240, v72, vcc
	v_cmp_lt_u32_e32 vcc, s54, v100
	v_add_u32_e32 v100, 16, v199
	s_nop 0
	v_cndmask_b32_e32 v89, v240, v89, vcc
	v_cmp_lt_u32_e32 vcc, s54, v100
	v_add_u32_e32 v100, 43, v199
	s_nop 0
	v_cndmask_b32_e32 v73, v240, v73, vcc
	v_cmp_lt_u32_e32 vcc, s54, v100
	v_add_u32_e32 v100, 11, v199
	s_nop 0
	v_cndmask_b32_e32 v90, v240, v90, vcc
	v_cmp_lt_u32_e32 vcc, s54, v100
	v_add_u32_e32 v100, 42, v199
	s_nop 0
	v_cndmask_b32_e32 v74, v240, v74, vcc
	v_cmp_lt_u32_e32 vcc, s54, v100
	v_add_u32_e32 v100, 10, v199
	s_nop 0
	v_cndmask_b32_e32 v91, v240, v91, vcc
	v_cmp_lt_u32_e32 vcc, s54, v100
	v_add_u32_e32 v100, 41, v199
	s_nop 0
	v_cndmask_b32_e32 v75, v240, v75, vcc
	v_cmp_lt_u32_e32 vcc, s54, v100
	v_add_u32_e32 v100, 9, v199
	s_nop 0
	v_cndmask_b32_e32 v92, v240, v92, vcc
	v_cmp_lt_u32_e32 vcc, s54, v100
	v_add_u32_e32 v100, 40, v199
	s_nop 0
	v_cndmask_b32_e32 v76, v240, v76, vcc
	v_cmp_lt_u32_e32 vcc, s54, v100
	v_add_u32_e32 v100, 8, v199
	s_nop 0
	v_cndmask_b32_e32 v93, v240, v93, vcc
	v_cmp_lt_u32_e32 vcc, s54, v100
	v_add_u32_e32 v100, 35, v199
	s_nop 0
	v_cndmask_b32_e32 v77, v240, v77, vcc
	v_cmp_lt_u32_e32 vcc, s54, v100
	v_add_u32_e32 v100, 3, v199
	s_nop 0
	v_cndmask_b32_e32 v94, v240, v94, vcc
	v_cmp_lt_u32_e32 vcc, s54, v100
	v_add_u32_e32 v100, 34, v199
	s_nop 0
	v_cndmask_b32_e32 v78, v240, v78, vcc
	v_cmp_lt_u32_e32 vcc, s54, v100
	v_add_u32_e32 v100, 2, v199
	s_nop 0
	v_cndmask_b32_e32 v95, v240, v95, vcc
	v_cmp_lt_u32_e32 vcc, s54, v100
	v_add_u32_e32 v100, 33, v199
	s_nop 0
	v_cndmask_b32_e32 v79, v240, v79, vcc
	v_cmp_lt_u32_e32 vcc, s54, v100
	v_add_u32_e32 v100, 1, v199
	s_nop 0
	v_cndmask_b32_e32 v96, v240, v96, vcc
	v_cmp_lt_u32_e32 vcc, s54, v100
	v_add_u32_e32 v100, 32, v199
	s_nop 0
	v_cndmask_b32_e32 v80, v240, v80, vcc
	v_cmp_lt_u32_e32 vcc, s54, v100
	s_nop 1
	v_cndmask_b32_e32 v97, v240, v97, vcc
	v_cmp_lt_u32_e32 vcc, s54, v199
	s_nop 1
	v_cndmask_b32_e32 v81, v240, v81, vcc

; __device__ __forceinline__ void finishSM(f32x16& p0, f32x16& p1, float alpha, float& l_reg, bf16x8& pa0, bf16x8& pa1, bf16x8& pa2, bf16x8& pa3) {
;     for (int r = 0; r < 16; ++r) p1[r] = __builtin_amdgcn_exp2f(p1[r]);
;     typedef float f32x8_ __attribute__((ext_vector_type(8))); typedef float f32x2_ __attribute__((ext_vector_type(2)));
;     const f32x16 s16 = p0 + p1; const f32x8_ s8 = s16.lo + s16.hi; const f32x4 s4 = s8.lo + s8.hi; const f32x2_ s2 = s4.lo + s4.hi; float ps = s2.x + s2.y;
;     { auto rr = __builtin_amdgcn_permlane32_swap(__float_as_uint(ps), __float_as_uint(ps), false, false);
;       ps = __uint_as_float(rr[0]) + __uint_as_float(rr[1]); }
;     l_reg = l_reg * alpha + ps;
;     ...
;     PK4(p0, 0, pa0); PK4(p0, 8, pa1); PK4(p1, 0, pa2); PK4(p1, 8, pa3);
;     ...
; }
; template <int KB, bool SK>
; __device__ __forceinline__ void qkt(f32x16& p0, f32x16& p1, const char* K_lds, int r32, int hi, const bf16x8* qr, bool act, const char* fb) {
;     if (SK && !act) { const float NEG = -__builtin_inff();
; #pragma unroll
;         for (int r = 0; r < 16; ++r) { p0[r] = NEG; p1[r] = NEG; } return; }
; #pragma unroll
;     for (int q = 0; q < 4; ++q) { const f32x4 b0 = *reinterpret_cast<const f32x4*>(fb + q * 32), b1 = *reinterpret_cast<const f32x4*>(fb + 128 + q * 32);
; #pragma unroll
;         for (int i = 0; i < 4; ++i) { p0[4 * q + i] = b0[i]; p1[4 * q + i] = b1[i]; } }
;     const char* kb[4];
; #pragma unroll
;     for (int dd = 0; dd < 4; ++dd) kb[dd] = K_lds + KB * SHM_K + KSWZ(r32, (dd * 16 + hi * 8) * 2);
;     if (MK_ATTPRIO) __builtin_amdgcn_s_setprio(1);
; #pragma unroll
;     for (int d0 = 0; d0 < 8; ++d0) { const char* a = kb[d0 & 3] + (d0 >> 2) * 128;
;         bf16x8 b0 = *reinterpret_cast<const bf16x8*>(a);
;         bf16x8 b1 = *reinterpret_cast<const bf16x8*>(a + 32 * 256);
;         p0 = __builtin_amdgcn_mfma_f32_32x32x16_bf16(b0, qr[d0], p0, 0, 0, 0);
;         p1 = __builtin_amdgcn_mfma_f32_32x32x16_bf16(b1, qr[d0], p1, 0, 0, 0); }
;     if (MK_ATTPRIO) __builtin_amdgcn_s_setprio(0);
; }
; template <bool SK>
; __device__ __forceinline__ void qkt_x(f32x16& p0, f32x16& p1, const char* K_lds, int r32, int hi, const bf16x8* qr, bool act, const char* fb) {
.LBB0_1001:
	v_sub_co_u32_e64 v67, s[0:1], s31, 1
	s_and_b64 s[0:1], s[0:1], exec
	v_readfirstlane_b32 s0, v67
	s_cselect_b32 s0, 2, s0
	s_add_i32 s1, s31, s0
	s_sub_i32 s33, 3, s1
	s_lshl_b32 s19, s31, 14
	s_cmp_lg_u32 s73, -1
	s_cselect_b32 s1, s73, 0
	s_add_i32 s1, s1, s19
	v_add_u32_e32 v154, s1, v193
	ds_read_b128 v[150:153], v154 offset:0
	v_lshl_add_u32 v67, s18, 2, v192
	v_add_u32_e32 v155, s1, v194
	v_add_u32_e32 v156, s1, v195
	ds_read_b128 v[192:195], v154 offset:0x2000
	v_add_u32_e32 v159, s1, v196
	ds_read_b128 v[196:199], v155 offset:0
	ds_read_b128 v[200:203], v155 offset:0x2000
	ds_read_b128 v[204:207], v156 offset:0
	ds_read_b128 v[208:211], v156 offset:0x2000
	ds_read_b128 v[212:215], v159 offset:0
	v_add_u32_e32 v82, 0xffffff00, v67
	ds_read_b128 v[216:219], v159 offset:0x2000
	v_add_u32_e32 v83, 0xffffff80, v67
	v_add_u32_e32 v86, 0xffffff20, v67
	v_add_u32_e32 v87, 0xffffffa0, v67
	v_add_u32_e32 v90, 0xffffff40, v67
	v_subrev_u32_e32 v91, 64, v67
	v_add_u32_e32 v94, 0xffffff60, v67
	ds_read_b128 v[98:101], v82
	ds_read_b128 v[82:85], v83
	ds_read_b128 v[102:105], v86
	ds_read_b128 v[86:89], v87
	ds_read_b128 v[106:109], v90
	ds_read_b128 v[90:93], v91
	v_subrev_u32_e32 v67, 32, v67
	ds_read_b128 v[110:113], v94
	ds_read_b128 v[94:97], v67
	s_waitcnt lgkmcnt(12)
	s_waitcnt lgkmcnt(1)
	v_mfma_f32_32x32x16_bf16 v[98:113], v[150:153], v[142:145], v[98:113]
	s_waitcnt lgkmcnt(0)
	v_mfma_f32_32x32x16_bf16 v[82:97], v[192:195], v[142:145], v[82:97]
	v_mfma_f32_32x32x16_bf16 v[82:97], v[200:203], v[138:141], v[82:97]
	v_mfma_f32_32x32x16_bf16 v[98:113], v[196:199], v[138:141], v[98:113]
	ds_read_b128 v[138:141], v154 offset:0x80
	ds_read_b128 v[142:145], v154 offset:0x2080
	ds_read_b128 v[150:153], v155 offset:0x80
	ds_read_b128 v[192:195], v155 offset:0x2080
	s_waitcnt lgkmcnt(4)
	s_nop 0
	v_mfma_f32_32x32x16_bf16 v[98:113], v[204:207], v[134:137], v[98:113]
	v_mfma_f32_32x32x16_bf16 v[98:113], v[212:215], v[130:133], v[98:113]
	v_mfma_f32_32x32x16_bf16 v[82:97], v[208:211], v[134:137], v[82:97]
	v_mfma_f32_32x32x16_bf16 v[82:97], v[216:219], v[130:133], v[82:97]
	ds_read_b128 v[130:133], v156 offset:0x80
	ds_read_b128 v[134:137], v156 offset:0x2080
	ds_read_b128 v[196:199], v159 offset:0x80
	ds_read_b128 v[200:203], v159 offset:0x2080
	s_waitcnt lgkmcnt(4)
	s_nop 0
	s_waitcnt lgkmcnt(0)
	v_mfma_f32_32x32x16_bf16 v[98:113], v[138:141], v[126:129], v[98:113]
	v_mfma_f32_32x32x16_bf16 v[98:113], v[150:153], v[122:125], v[98:113]
	v_mfma_f32_32x32x16_bf16 v[98:113], v[130:133], v[118:121], v[98:113]
	v_mfma_f32_32x32x16_bf16 v[98:113], v[196:199], v[114:117], v[98:113]
	v_mfma_f32_32x32x16_bf16 v[82:97], v[142:145], v[126:129], v[82:97]
	v_mfma_f32_32x32x16_bf16 v[82:97], v[192:195], v[122:125], v[82:97]
	v_mfma_f32_32x32x16_bf16 v[82:97], v[134:137], v[118:121], v[82:97]
	v_mfma_f32_32x32x16_bf16 v[82:97], v[200:203], v[114:117], v[82:97]
	s_lshl_b32 s1, s33, 14
	s_add_i32 s24, s1, s24
	s_mov_b32 m0, s24
	s_add_i32 s1, s1, s20
	global_load_lds_dwordx4 v147, s[62:63]
	s_add_i32 m0, s24, 0x400
	v_lshl_add_u64 v[114:115], s[64:65], 0, v[182:183]
	global_load_lds_dwordx4 v149, s[62:63]
	s_mov_b32 m0, s1
	v_lshl_add_u64 v[114:115], v[114:115], 0, s[28:29]
	global_load_lds_dwordx4 v182, s[64:65]
	s_add_i32 m0, s1, 0x400
	s_nop 0
	global_load_lds_dwordx4 v[114:115], off
	v_ashrrev_i32_e32 v147, 31, v146
	v_lshlrev_b64 v[114:115], 8, v[146:147]
	v_lshl_add_u64 v[114:115], s[10:11], 0, v[114:115]
	v_mov_b32_e32 v149, v183
	v_lshl_add_u64 v[114:115], v[114:115], 0, v[148:149]
	global_load_dwordx4 v[142:145], v[114:115], off
	global_load_dwordx4 v[138:141], v[114:115], off offset:32
	global_load_dwordx4 v[134:137], v[114:115], off offset:64
	global_load_dwordx4 v[130:133], v[114:115], off offset:96
	global_load_dwordx4 v[126:129], v[114:115], off offset:128
	global_load_dwordx4 v[122:125], v[114:115], off offset:160
	global_load_dwordx4 v[118:121], v[114:115], off offset:192
	s_nop 0
	global_load_dwordx4 v[114:117], v[114:115], off offset:224
	v_exp_f32_e32 v148, v66
	v_exp_f32_e32 v149, v1
	v_exp_f32_e32 v150, v68
	v_exp_f32_e32 v151, v69
	v_exp_f32_e32 v152, v70
	v_exp_f32_e32 v153, v71
	v_exp_f32_e32 v154, v72
	v_exp_f32_e32 v155, v73
	v_exp_f32_e32 v180, v74
	v_exp_f32_e32 v181, v75
	v_exp_f32_e32 v184, v76
	v_exp_f32_e32 v185, v77
	v_exp_f32_e32 v186, v78
	v_exp_f32_e32 v80, v80
	v_exp_f32_e32 v81, v81
	v_exp_f32_e32 v187, v79
	v_pk_add_f32 v[66:67], v[166:167], v[184:185]
	v_pk_add_f32 v[68:69], v[176:177], v[150:151]
	v_pk_add_f32 v[70:71], v[162:163], v[80:81]
	v_pk_add_f32 v[72:73], v[172:173], v[154:155]
	v_pk_add_f32 v[74:75], v[168:169], v[180:181]
	v_pk_add_f32 v[76:77], v[178:179], v[148:149]
	v_pk_add_f32 v[78:79], v[164:165], v[186:187]
	v_pk_add_f32 v[188:189], v[174:175], v[152:153]
	v_pk_add_f32 v[74:75], v[76:77], v[74:75]
	v_pk_add_f32 v[78:79], v[188:189], v[78:79]
	v_pk_add_f32 v[70:71], v[72:73], v[70:71]
	v_pk_add_f32 v[66:67], v[68:69], v[66:67]
	v_pk_add_f32 v[68:69], v[74:75], v[78:79]
	v_pk_add_f32 v[66:67], v[66:67], v[70:71]
	s_nop 0
	v_pk_add_f32 v[66:67], v[68:69], v[66:67]
	v_cvt_pk_bf16_f32 v68, v178, v179
	v_cvt_pk_bf16_f32 v69, v176, v177
	v_cvt_pk_bf16_f32 v70, v174, v175
	v_cvt_pk_bf16_f32 v71, v172, v173
	v_cvt_pk_bf16_f32 v72, v168, v169
	s_nop 0
	v_pk_add_f32 v[66:67], v[66:67], v[66:67] op_sel:[0,1] op_sel_hi:[1,0]
	v_cvt_pk_bf16_f32 v73, v166, v167
	v_cvt_pk_bf16_f32 v74, v164, v165
	v_cvt_pk_bf16_f32 v75, v162, v163
	v_cvt_pk_bf16_f32 v76, v148, v149
	v_cvt_pk_bf16_f32 v77, v150, v151
	s_nop 0
	v_mov_b32_e32 v1, v66
	s_nop 1
	v_permlane32_swap_b32_e32 v66, v1
	v_cvt_pk_bf16_f32 v78, v152, v153
	v_cvt_pk_bf16_f32 v79, v154, v155
	v_cvt_pk_bf16_f32 v148, v180, v181
	v_cvt_pk_bf16_f32 v149, v184, v185
	v_cvt_pk_bf16_f32 v150, v186, v187
	v_cvt_pk_bf16_f32 v151, v80, v81
	v_permlane32_swap_b32_e32 v68, v70
	v_permlane32_swap_b32_e32 v69, v71
	v_permlane32_swap_b32_e32 v72, v74
	v_permlane32_swap_b32_e32 v73, v75
	v_permlane32_swap_b32_e32 v76, v78
	v_permlane32_swap_b32_e32 v77, v79
	v_permlane32_swap_b32_e32 v148, v150
	v_permlane32_swap_b32_e32 v149, v151
	v_lshl_add_u32 v67, s0, 14, v171
	ds_read_b64_tr_b16 v[152:153], v67 offset:0
	ds_read_b64_tr_b16 v[154:155], v67 offset:0x800
	ds_read_b64_tr_b16 v[162:163], v67 offset:0x1000
	ds_read_b64_tr_b16 v[164:165], v67 offset:0x1800
	ds_read_b64_tr_b16 v[166:167], v67 offset:0x2000
	ds_read_b64_tr_b16 v[168:169], v67 offset:0x2800
	ds_read_b64_tr_b16 v[172:173], v67 offset:0x3000
	ds_read_b64_tr_b16 v[174:175], v67 offset:0x3800
	ds_read_b64_tr_b16 v[176:177], v67 offset:0x200
	ds_read_b64_tr_b16 v[178:179], v67 offset:0xa00
	ds_read_b64_tr_b16 v[192:193], v67 offset:0x1200
	ds_read_b64_tr_b16 v[194:195], v67 offset:0x1a00
	ds_read_b64_tr_b16 v[196:197], v67 offset:0x2200
	ds_read_b64_tr_b16 v[198:199], v67 offset:0x2a00
	ds_read_b64_tr_b16 v[200:201], v67 offset:0x3200
	ds_read_b64_tr_b16 v[202:203], v67 offset:0x3a00
	s_nop 0
	s_waitcnt lgkmcnt(8)
; #define PV_LD(R, d0) do { constexpr int b_ = v_rd_off(d0, 0, 0); TRRD(R##0, b_); TRRD(R##1, b_ + 2048); TRRD(R##2, b_ + 4096); TRRD(R##3, b_ + 6144); TRRD(R##4, b_ + 8192); TRRD(R##5, b_ + 10240); TRRD(R##6, b_ + 12288); TRRD(R##7, b_ + 14336); } while (0)
; #define PV_MM(R, d0) do { o[d0] = __builtin_amdgcn_mfma_f32_32x32x16_bf16(PV_J(R##0, R##1), pa0, o[d0], 0, 0, 0); o[d0] = __builtin_amdgcn_mfma_f32_32x32x16_bf16(PV_J(R##2, R##3), pa1, o[d0], 0, 0, 0); \
;         o[d0] = __builtin_amdgcn_mfma_f32_32x32x16_bf16(PV_J(R##4, R##5), pa2, o[d0], 0, 0, 0); o[d0] = __builtin_amdgcn_mfma_f32_32x32x16_bf16(PV_J(R##6, R##7), pa3, o[d0], 0, 0, 0); } while (0)
; #define PV_W(n, R) asm volatile("s_waitcnt lgkmcnt(" #n ")" : "+v"(R##0), "+v"(R##1), "+v"(R##2), "+v"(R##3), "+v"(R##4), "+v"(R##5), "+v"(R##6), "+v"(R##7) :: "memory")
; __device__ __forceinline__ void mask_tile(f32x16& p0, f32x16& p1, int dq, unsigned W) {
;     const float NEG = -__builtin_inff();
; #pragma unroll
;     for (int r = 0; r < 16; ++r) {
;         const int c = (r & 3) + 8 * (r >> 2);
;         if ((unsigned)(dq - c) >= W) p0[r] = NEG;
;         if ((unsigned)(dq - c - 32) >= W) p1[r] = NEG;
;     }
; }
; template <bool SK>
; __device__ __forceinline__ void pv_tile_x(f32x16* o, int vb, bf16x8 pa0, bf16x8 pa1, bf16x8 pa2, bf16x8 pa3, bool act) {
;     if (SK && !act) return;
;     ...
;     s16x4 fa0, fa1, fa2, fa3, fa4, fa5, fa6, fa7, fb0, fb1, fb2, fb3, fb4, fb5, fb6, fb7;
;     PV_LD(fa, 0); PV_LD(fb, 1);
;     PV_W(8, fa); PV_MM(fa, 0); PV_LD(fa, 2);
;     PV_W(8, fb); PV_MM(fb, 1); PV_LD(fb, 3);
;     PV_W(8, fa); PV_MM(fa, 2);
;     PV_W(0, fb); PV_MM(fb, 3);
	s_cmp_lt_i32 s30, 8
	v_mfma_f32_32x32x16_bf16 v[50:65], v[152:155], v[68:71], v[50:65]
	ds_read_b64_tr_b16 v[152:153], v67 offset:0x400
	ds_read_b64_tr_b16 v[154:155], v67 offset:0xc00
	v_mfma_f32_32x32x16_bf16 v[50:65], v[162:165], v[72:75], v[50:65]
	ds_read_b64_tr_b16 v[162:163], v67 offset:0x1400
	ds_read_b64_tr_b16 v[164:165], v67 offset:0x1c00
	v_mfma_f32_32x32x16_bf16 v[50:65], v[166:169], v[76:79], v[50:65]
	ds_read_b64_tr_b16 v[166:167], v67 offset:0x2400
	ds_read_b64_tr_b16 v[168:169], v67 offset:0x2c00
	v_mfma_f32_32x32x16_bf16 v[50:65], v[172:175], v[148:151], v[50:65]
	ds_read_b64_tr_b16 v[172:173], v67 offset:0x3400
	ds_read_b64_tr_b16 v[174:175], v67 offset:0x3c00
	s_waitcnt lgkmcnt(8)
	s_nop 0
	v_mfma_f32_32x32x16_bf16 v[34:49], v[176:179], v[68:71], v[34:49]
	ds_read_b64_tr_b16 v[176:177], v67 offset:0x600
	ds_read_b64_tr_b16 v[178:179], v67 offset:0xe00
	v_mfma_f32_32x32x16_bf16 v[34:49], v[192:195], v[72:75], v[34:49]
	ds_read_b64_tr_b16 v[192:193], v67 offset:0x1600
	ds_read_b64_tr_b16 v[194:195], v67 offset:0x1e00
	v_mfma_f32_32x32x16_bf16 v[34:49], v[196:199], v[76:79], v[34:49]
	ds_read_b64_tr_b16 v[196:197], v67 offset:0x2600
	ds_read_b64_tr_b16 v[198:199], v67 offset:0x2e00
	v_mfma_f32_32x32x16_bf16 v[34:49], v[200:203], v[148:151], v[34:49]
	ds_read_b64_tr_b16 v[200:201], v67 offset:0x3600
	ds_read_b64_tr_b16 v[202:203], v67 offset:0x3e00
	s_waitcnt lgkmcnt(8)
	s_nop 0
	s_waitcnt lgkmcnt(0)
	v_mfma_f32_32x32x16_bf16 v[18:33], v[152:155], v[68:71], v[18:33]
	v_mfma_f32_32x32x16_bf16 v[18:33], v[162:165], v[72:75], v[18:33]
	v_mfma_f32_32x32x16_bf16 v[18:33], v[166:169], v[76:79], v[18:33]
	v_mfma_f32_32x32x16_bf16 v[18:33], v[172:175], v[148:151], v[18:33]
	v_mfma_f32_32x32x16_bf16 v[2:17], v[176:179], v[68:71], v[2:17]
	v_mfma_f32_32x32x16_bf16 v[2:17], v[192:195], v[72:75], v[2:17]
	v_mfma_f32_32x32x16_bf16 v[2:17], v[196:199], v[76:79], v[2:17]
	v_mfma_f32_32x32x16_bf16 v[2:17], v[200:203], v[148:151], v[2:17]
	s_cbranch_scc0 .LBB0_1003
	v_subrev_u32_e32 v67, s18, v190
	v_add_u32_e32 v68, 0xfffff040, v67
	v_cmp_lt_u32_e32 vcc, s54, v68
	v_add_u32_e32 v68, 0xfffff020, v67
	s_nop 0
	v_cndmask_b32_e32 v98, v240, v98, vcc
	v_cmp_lt_u32_e32 vcc, s54, v68
	v_add_u32_e32 v68, 0xfffff03f, v67
	s_nop 0
	v_cndmask_b32_e32 v82, v240, v82, vcc
	v_cmp_lt_u32_e32 vcc, s54, v68
	v_add_u32_e32 v68, 0xfffff01f, v67
	s_nop 0
	v_cndmask_b32_e32 v99, v240, v99, vcc
	v_cmp_lt_u32_e32 vcc, s54, v68
	v_add_u32_e32 v68, 0xfffff03e, v67
	s_nop 0
	v_cndmask_b32_e32 v83, v240, v83, vcc
	v_cmp_lt_u32_e32 vcc, s54, v68
	v_add_u32_e32 v68, 0xfffff01e, v67
	s_nop 0
	v_cndmask_b32_e32 v100, v240, v100, vcc
	v_cmp_lt_u32_e32 vcc, s54, v68
	v_add_u32_e32 v68, 0xfffff03d, v67
	s_nop 0
	v_cndmask_b32_e32 v84, v240, v84, vcc
	v_cmp_lt_u32_e32 vcc, s54, v68
	v_add_u32_e32 v68, 0xfffff01d, v67
	s_nop 0
	v_cndmask_b32_e32 v101, v240, v101, vcc
	v_cmp_lt_u32_e32 vcc, s54, v68
	v_add_u32_e32 v68, 0xfffff038, v67
	s_nop 0
	v_cndmask_b32_e32 v85, v240, v85, vcc
	v_cmp_lt_u32_e32 vcc, s54, v68
	v_add_u32_e32 v68, 0xfffff018, v67
	s_nop 0
	v_cndmask_b32_e32 v102, v240, v102, vcc
	v_cmp_lt_u32_e32 vcc, s54, v68
	v_add_u32_e32 v68, 0xfffff037, v67
	s_nop 0
	v_cndmask_b32_e32 v86, v240, v86, vcc
	v_cmp_lt_u32_e32 vcc, s54, v68
	v_add_u32_e32 v68, 0xfffff017, v67
	s_nop 0
	v_cndmask_b32_e32 v103, v240, v103, vcc
	v_cmp_lt_u32_e32 vcc, s54, v68
	v_add_u32_e32 v68, 0xfffff036, v67
	s_nop 0
	v_cndmask_b32_e32 v87, v240, v87, vcc
	v_cmp_lt_u32_e32 vcc, s54, v68
	v_add_u32_e32 v68, 0xfffff016, v67
	s_nop 0
	v_cndmask_b32_e32 v104, v240, v104, vcc
	v_cmp_lt_u32_e32 vcc, s54, v68
	v_add_u32_e32 v68, 0xfffff035, v67
	s_nop 0
	v_cndmask_b32_e32 v88, v240, v88, vcc
	v_cmp_lt_u32_e32 vcc, s54, v68
	v_add_u32_e32 v68, 0xfffff015, v67
	s_nop 0
	v_cndmask_b32_e32 v105, v240, v105, vcc
	v_cmp_lt_u32_e32 vcc, s54, v68
	v_add_u32_e32 v68, 0xfffff030, v67
	s_nop 0
	v_cndmask_b32_e32 v89, v240, v89, vcc
	v_cmp_lt_u32_e32 vcc, s54, v68
	v_add_u32_e32 v68, 0xfffff010, v67
	s_nop 0
	v_cndmask_b32_e32 v106, v240, v106, vcc
	v_cmp_lt_u32_e32 vcc, s54, v68
	v_add_u32_e32 v68, 0xfffff02f, v67
	s_nop 0
	v_cndmask_b32_e32 v90, v240, v90, vcc
	v_cmp_lt_u32_e32 vcc, s54, v68
	v_add_u32_e32 v68, 0xfffff00f, v67
	s_nop 0
	v_cndmask_b32_e32 v107, v240, v107, vcc
	v_cmp_lt_u32_e32 vcc, s54, v68
	v_add_u32_e32 v68, 0xfffff02e, v67
	s_nop 0
	v_cndmask_b32_e32 v91, v240, v91, vcc
	v_cmp_lt_u32_e32 vcc, s54, v68
	v_add_u32_e32 v68, 0xfffff00e, v67
	s_nop 0
	v_cndmask_b32_e32 v108, v240, v108, vcc
	v_cmp_lt_u32_e32 vcc, s54, v68
	v_add_u32_e32 v68, 0xfffff02d, v67
	s_nop 0
	v_cndmask_b32_e32 v92, v240, v92, vcc
	v_cmp_lt_u32_e32 vcc, s54, v68
	v_add_u32_e32 v68, 0xfffff00d, v67
	s_nop 0
	v_cndmask_b32_e32 v109, v240, v109, vcc
	v_cmp_lt_u32_e32 vcc, s54, v68
	v_add_u32_e32 v68, 0xfffff028, v67
	s_nop 0
	v_cndmask_b32_e32 v93, v240, v93, vcc
	v_cmp_lt_u32_e32 vcc, s54, v68
	v_add_u32_e32 v68, 0xfffff008, v67
	s_nop 0
	v_cndmask_b32_e32 v110, v240, v110, vcc
	v_cmp_lt_u32_e32 vcc, s54, v68
	v_add_u32_e32 v68, 0xfffff027, v67
	s_nop 0
	v_cndmask_b32_e32 v94, v240, v94, vcc
	v_cmp_lt_u32_e32 vcc, s54, v68
	v_add_u32_e32 v68, 0xfffff007, v67
	s_nop 0
	v_cndmask_b32_e32 v111, v240, v111, vcc
	v_cmp_lt_u32_e32 vcc, s54, v68
	v_add_u32_e32 v68, 0xfffff026, v67
	s_nop 0
	v_cndmask_b32_e32 v95, v240, v95, vcc
	v_cmp_lt_u32_e32 vcc, s54, v68
	v_add_u32_e32 v68, 0xfffff006, v67
	s_nop 0
	v_cndmask_b32_e32 v112, v240, v112, vcc
	v_cmp_lt_u32_e32 vcc, s54, v68
	v_add_u32_e32 v68, 0xfffff025, v67
	v_add_u32_e32 v67, 0xfffff005, v67
	v_cndmask_b32_e32 v96, v240, v96, vcc
	v_cmp_lt_u32_e32 vcc, s54, v68
	s_nop 1
	v_cndmask_b32_e32 v113, v240, v113, vcc
	v_cmp_lt_u32_e32 vcc, s54, v67
	s_nop 1
	v_cndmask_b32_e32 v97, v240, v97, vcc
